# RWKV scan chunk body hand-scheduled (fewer instrs, batched y reduction, counted vmcnt); rwkv_prep sub-pass bias load hoisted
# speedup vs baseline: 1.0955x; 1.0258x over previous
.LBB0_517:
	s_cmp_lt_u32 s7, 4
	s_cselect_b64 s[4:5], -1, 0
	v_readlane_b32 s12, v255, 61
	s_and_b64 s[8:9], s[4:5], exec
	v_readlane_b32 s20, v254, 5
	v_readlane_b32 s21, v254, 6
	v_readlane_b32 s22, v254, 7
	v_readlane_b32 s23, v254, 8
	s_cselect_b32 s8, s20, s22
	s_cselect_b32 s9, s21, s23
	s_and_b32 s33, s6, 0x60
	v_or_b32_e32 v18, s33, v22
	v_ashrrev_i32_e32 v19, 31, v18
	v_lshlrev_b64 v[0:1], 7, v[18:19]
	v_lshl_add_u64 v[0:1], s[8:9], 0, v[0:1]
	v_lshl_add_u64 v[4:5], v[0:1], 0, v[42:43]
	global_load_dwordx4 v[0:3], v[4:5], off
	global_load_dwordx4 v[24:27], v[4:5], off offset:32
	global_load_dwordx4 v[28:31], v[4:5], off offset:64
	global_load_dwordx4 v[32:35], v[4:5], off offset:96
	v_readlane_b32 s98, v255, 33
	v_readlane_b32 s99, v255, 34
	v_readlane_b32 s100, v255, 37
	v_readlane_b32 s101, v255, 38
	s_cmp_gt_u32 s7, 3
	s_cselect_b32 s98, s100, s98
	s_cselect_b32 s99, s101, s99
	v_lshl_add_u64 v[84:85], v[18:19], 2, s[98:99]
	global_load_dword v86, v[84:85], off
	s_and_b64 s[4:5], s[4:5], exec
	s_cselect_b32 s4, 0, 0x1200
	v_add3_u32 v23, s4, v20, v42
	ds_read_b128 v[4:7], v23
	ds_read_b128 v[36:39], v23 offset:32
	s_cmp_gt_u32 s7, 3
	s_mov_b64 s[4:5], -1
	v_readlane_b32 s13, v255, 62
	v_readlane_b32 s14, v255, 63
	v_readlane_b32 s15, v254, 0
	v_readlane_b32 s16, v254, 1
	v_readlane_b32 s17, v254, 2
	v_readlane_b32 s18, v254, 3
	v_readlane_b32 s19, v254, 4
	v_readlane_b32 s24, v254, 9
	v_readlane_b32 s25, v254, 10
	v_readlane_b32 s26, v254, 11
	v_readlane_b32 s27, v254, 12
	s_waitcnt vmcnt(4) lgkmcnt(1)
	v_mfma_f32_32x32x16_bf16 v[0:15], v[4:7], v[0:3], 0
	s_waitcnt vmcnt(3) lgkmcnt(0)
	v_mfma_f32_32x32x16_bf16 v[0:15], v[36:39], v[24:27], v[0:15]
	ds_read_b128 v[24:27], v23 offset:64
	s_waitcnt vmcnt(2) lgkmcnt(0)
	v_mfma_f32_32x32x16_bf16 v[0:15], v[24:27], v[28:31], v[0:15]
	ds_read_b128 v[24:27], v23 offset:96
	s_waitcnt vmcnt(1) lgkmcnt(0)
	v_mfma_f32_32x32x16_bf16 v[0:15], v[24:27], v[32:35], v[0:15]
	s_cbranch_scc1 .LBB0_519
	s_andn2_b64 vcc, exec, s[4:5]
	s_cbranch_vccnz .LBB0_516
	s_branch .LBB0_520
.LBB0_519:
	v_readlane_b32 s12, v255, 29
	v_readlane_b32 s20, v255, 37
	v_readlane_b32 s21, v255, 38
	v_readlane_b32 s13, v255, 30
	v_readlane_b32 s14, v255, 31
	v_lshl_add_u64 v[24:25], v[18:19], 2, s[20:21]
	v_readlane_b32 s15, v255, 32
	v_readlane_b32 s16, v255, 33
	v_readlane_b32 s17, v255, 34
	v_readlane_b32 s18, v255, 35
	v_readlane_b32 s19, v255, 36
	v_readlane_b32 s22, v255, 39
	v_readlane_b32 s23, v255, 40
	v_readlane_b32 s24, v255, 41
	v_readlane_b32 s25, v255, 42
	v_readlane_b32 s26, v255, 43
	v_readlane_b32 s27, v255, 44
	s_waitcnt vmcnt(0)
	v_add_f32_e32 v24, v0, v86
	v_mul_f32_e32 v24, 0xbfb8aa3b, v24
	v_exp_f32_e32 v24, v24
	s_nop 0
	v_add_f32_e32 v24, 1.0, v24
	v_div_scale_f32 v25, s[4:5], v24, v24, 1.0
	v_rcp_f32_e32 v26, v25
	s_nop 0
	v_fma_f32 v27, -v25, v26, 1.0
	v_fmac_f32_e32 v26, v27, v26
	v_div_scale_f32 v27, vcc, 1.0, v24, 1.0
	v_mul_f32_e32 v28, v27, v26
	v_fma_f32 v29, -v25, v28, v27
	v_fmac_f32_e32 v28, v29, v26
	v_fma_f32 v25, -v25, v28, v27
	v_div_fmas_f32 v25, v25, v26, v28
	v_div_fixup_f32 v24, v25, v24, 1.0
	v_cvt_pk_bf16_f32 v25, v24, s0
	v_lshl_add_u32 v24, v18, 1, v21
	ds_write_b16 v24, v25 offset:9216
	v_add_f32_e32 v25, v1, v86
	v_mul_f32_e32 v25, 0xbfb8aa3b, v25
	v_exp_f32_e32 v25, v25
	s_nop 0
	v_add_f32_e32 v25, 1.0, v25
	v_div_scale_f32 v26, s[4:5], v25, v25, 1.0
	v_rcp_f32_e32 v27, v26
	s_nop 0
	v_fma_f32 v28, -v26, v27, 1.0
	v_fmac_f32_e32 v27, v28, v27
	v_div_scale_f32 v28, vcc, 1.0, v25, 1.0
	v_mul_f32_e32 v29, v28, v27
	v_fma_f32 v30, -v26, v29, v28
	v_fmac_f32_e32 v29, v30, v27
	v_fma_f32 v26, -v26, v29, v28
	v_div_fmas_f32 v26, v26, v27, v29
	v_div_fixup_f32 v25, v26, v25, 1.0
	v_cvt_pk_bf16_f32 v25, v25, s0
	ds_write_b16 v24, v25 offset:10256
	v_add_f32_e32 v25, v2, v86
	v_mul_f32_e32 v25, 0xbfb8aa3b, v25
	v_exp_f32_e32 v25, v25
	s_nop 0
	v_add_f32_e32 v25, 1.0, v25
	v_div_scale_f32 v26, s[4:5], v25, v25, 1.0
	v_rcp_f32_e32 v27, v26
	s_nop 0
	v_fma_f32 v28, -v26, v27, 1.0
	v_fmac_f32_e32 v27, v28, v27
	v_div_scale_f32 v28, vcc, 1.0, v25, 1.0
	v_mul_f32_e32 v29, v28, v27
	v_fma_f32 v30, -v26, v29, v28
	v_fmac_f32_e32 v29, v30, v27
	v_fma_f32 v26, -v26, v29, v28
	v_div_fmas_f32 v26, v26, v27, v29
	v_div_fixup_f32 v25, v26, v25, 1.0
	v_cvt_pk_bf16_f32 v25, v25, s0
	ds_write_b16 v24, v25 offset:11296
	v_add_f32_e32 v25, v3, v86
	v_mul_f32_e32 v25, 0xbfb8aa3b, v25
	v_exp_f32_e32 v25, v25
	s_nop 0
	v_add_f32_e32 v25, 1.0, v25
	v_div_scale_f32 v26, s[4:5], v25, v25, 1.0
	v_rcp_f32_e32 v27, v26
	s_nop 0
	v_fma_f32 v28, -v26, v27, 1.0
	v_fmac_f32_e32 v27, v28, v27
	v_div_scale_f32 v28, vcc, 1.0, v25, 1.0
	v_mul_f32_e32 v29, v28, v27
	v_fma_f32 v30, -v26, v29, v28
	v_fmac_f32_e32 v29, v30, v27
	v_fma_f32 v26, -v26, v29, v28
	v_div_fmas_f32 v26, v26, v27, v29
	v_div_fixup_f32 v25, v26, v25, 1.0
	v_cvt_pk_bf16_f32 v25, v25, s0
	ds_write_b16 v24, v25 offset:12336
	v_add_f32_e32 v25, v4, v86
	v_mul_f32_e32 v25, 0xbfb8aa3b, v25
	v_exp_f32_e32 v25, v25
	s_nop 0
	v_add_f32_e32 v25, 1.0, v25
	v_div_scale_f32 v26, s[4:5], v25, v25, 1.0
	v_rcp_f32_e32 v27, v26
	s_nop 0
	v_fma_f32 v28, -v26, v27, 1.0
	v_fmac_f32_e32 v27, v28, v27
	v_div_scale_f32 v28, vcc, 1.0, v25, 1.0
	v_mul_f32_e32 v29, v28, v27
	v_fma_f32 v30, -v26, v29, v28
	v_fmac_f32_e32 v29, v30, v27
	v_fma_f32 v26, -v26, v29, v28
	v_div_fmas_f32 v26, v26, v27, v29
	v_div_fixup_f32 v25, v26, v25, 1.0
	v_cvt_pk_bf16_f32 v25, v25, s0
	ds_write_b16 v24, v25 offset:17536
	v_add_f32_e32 v25, v5, v86
	v_mul_f32_e32 v25, 0xbfb8aa3b, v25
	v_exp_f32_e32 v25, v25
	s_nop 0
	v_add_f32_e32 v25, 1.0, v25
	v_div_scale_f32 v26, s[4:5], v25, v25, 1.0
	v_rcp_f32_e32 v27, v26
	s_nop 0
	v_fma_f32 v28, -v26, v27, 1.0
	v_fmac_f32_e32 v27, v28, v27
	v_div_scale_f32 v28, vcc, 1.0, v25, 1.0
	v_mul_f32_e32 v29, v28, v27
	v_fma_f32 v30, -v26, v29, v28
	v_fmac_f32_e32 v29, v30, v27
	v_fma_f32 v26, -v26, v29, v28
	v_div_fmas_f32 v26, v26, v27, v29
	v_div_fixup_f32 v25, v26, v25, 1.0
	v_cvt_pk_bf16_f32 v25, v25, s0
	ds_write_b16 v24, v25 offset:18576
	v_add_f32_e32 v25, v6, v86
	v_mul_f32_e32 v25, 0xbfb8aa3b, v25
	v_exp_f32_e32 v25, v25
	s_nop 0
	v_add_f32_e32 v25, 1.0, v25
	v_div_scale_f32 v26, s[4:5], v25, v25, 1.0
	v_rcp_f32_e32 v27, v26
	s_nop 0
	v_fma_f32 v28, -v26, v27, 1.0
	v_fmac_f32_e32 v27, v28, v27
	v_div_scale_f32 v28, vcc, 1.0, v25, 1.0
	v_mul_f32_e32 v29, v28, v27
	v_fma_f32 v30, -v26, v29, v28
	v_fmac_f32_e32 v29, v30, v27
	v_fma_f32 v26, -v26, v29, v28
	v_div_fmas_f32 v26, v26, v27, v29
	v_div_fixup_f32 v25, v26, v25, 1.0
	v_cvt_pk_bf16_f32 v25, v25, s0
	ds_write_b16 v24, v25 offset:19616
	v_add_f32_e32 v25, v7, v86
	v_mul_f32_e32 v25, 0xbfb8aa3b, v25
	v_exp_f32_e32 v25, v25
	s_nop 0
	v_add_f32_e32 v25, 1.0, v25
	v_div_scale_f32 v26, s[4:5], v25, v25, 1.0
	v_rcp_f32_e32 v27, v26
	s_nop 0
	v_fma_f32 v28, -v26, v27, 1.0
	v_fmac_f32_e32 v27, v28, v27
	v_div_scale_f32 v28, vcc, 1.0, v25, 1.0
	v_mul_f32_e32 v29, v28, v27
	v_fma_f32 v30, -v26, v29, v28
	v_fmac_f32_e32 v29, v30, v27
	v_fma_f32 v26, -v26, v29, v28
	v_div_fmas_f32 v26, v26, v27, v29
	v_div_fixup_f32 v25, v26, v25, 1.0
	v_cvt_pk_bf16_f32 v25, v25, s0
	ds_write_b16 v24, v25 offset:20656
	v_add_f32_e32 v25, v8, v86
	v_mul_f32_e32 v25, 0xbfb8aa3b, v25
	v_exp_f32_e32 v25, v25
	s_nop 0
	v_add_f32_e32 v25, 1.0, v25
	v_div_scale_f32 v26, s[4:5], v25, v25, 1.0
	v_rcp_f32_e32 v27, v26
	s_nop 0
	v_fma_f32 v28, -v26, v27, 1.0
	v_fmac_f32_e32 v27, v28, v27
	v_div_scale_f32 v28, vcc, 1.0, v25, 1.0
	v_mul_f32_e32 v29, v28, v27
	v_fma_f32 v30, -v26, v29, v28
	v_fmac_f32_e32 v29, v30, v27
	v_fma_f32 v26, -v26, v29, v28
	v_div_fmas_f32 v26, v26, v27, v29
	v_div_fixup_f32 v25, v26, v25, 1.0
	v_cvt_pk_bf16_f32 v25, v25, s0
	ds_write_b16 v24, v25 offset:25856
	v_add_f32_e32 v25, v9, v86
	v_mul_f32_e32 v25, 0xbfb8aa3b, v25
	v_exp_f32_e32 v25, v25
	s_nop 0
	v_add_f32_e32 v25, 1.0, v25
	v_div_scale_f32 v26, s[4:5], v25, v25, 1.0
	v_rcp_f32_e32 v27, v26
	s_nop 0
	v_fma_f32 v28, -v26, v27, 1.0
	v_fmac_f32_e32 v27, v28, v27
	v_div_scale_f32 v28, vcc, 1.0, v25, 1.0
	v_mul_f32_e32 v29, v28, v27
	v_fma_f32 v30, -v26, v29, v28
	v_fmac_f32_e32 v29, v30, v27
	v_fma_f32 v26, -v26, v29, v28
	v_div_fmas_f32 v26, v26, v27, v29
	v_div_fixup_f32 v25, v26, v25, 1.0
	v_cvt_pk_bf16_f32 v25, v25, s0
	ds_write_b16 v24, v25 offset:26896
	v_add_f32_e32 v25, v10, v86
	v_mul_f32_e32 v25, 0xbfb8aa3b, v25
	v_exp_f32_e32 v25, v25
	s_nop 0
	v_add_f32_e32 v25, 1.0, v25
	v_div_scale_f32 v26, s[4:5], v25, v25, 1.0
	v_rcp_f32_e32 v27, v26
	s_nop 0
	v_fma_f32 v28, -v26, v27, 1.0
	v_fmac_f32_e32 v27, v28, v27
	v_div_scale_f32 v28, vcc, 1.0, v25, 1.0
	v_mul_f32_e32 v29, v28, v27
	v_fma_f32 v30, -v26, v29, v28
	v_fmac_f32_e32 v29, v30, v27
	v_fma_f32 v26, -v26, v29, v28
	v_div_fmas_f32 v26, v26, v27, v29
	v_div_fixup_f32 v25, v26, v25, 1.0
	v_cvt_pk_bf16_f32 v25, v25, s0
	ds_write_b16 v24, v25 offset:27936
	v_add_f32_e32 v25, v11, v86
	v_mul_f32_e32 v25, 0xbfb8aa3b, v25
	v_exp_f32_e32 v25, v25
	s_nop 0
	v_add_f32_e32 v25, 1.0, v25
	v_div_scale_f32 v26, s[4:5], v25, v25, 1.0
	v_rcp_f32_e32 v27, v26
	s_nop 0
	v_fma_f32 v28, -v26, v27, 1.0
	v_fmac_f32_e32 v27, v28, v27
	v_div_scale_f32 v28, vcc, 1.0, v25, 1.0
	v_mul_f32_e32 v29, v28, v27
	v_fma_f32 v30, -v26, v29, v28
	v_fmac_f32_e32 v29, v30, v27
	v_fma_f32 v26, -v26, v29, v28
	v_div_fmas_f32 v26, v26, v27, v29
	v_div_fixup_f32 v25, v26, v25, 1.0
	v_cvt_pk_bf16_f32 v25, v25, s0
	ds_write_b16 v24, v25 offset:28976
	v_add_f32_e32 v25, v12, v86
	v_mul_f32_e32 v25, 0xbfb8aa3b, v25
	v_exp_f32_e32 v25, v25
	s_nop 0
	v_add_f32_e32 v25, 1.0, v25
	v_div_scale_f32 v26, s[4:5], v25, v25, 1.0
	v_rcp_f32_e32 v27, v26
	s_nop 0
	v_fma_f32 v28, -v26, v27, 1.0
	v_fmac_f32_e32 v27, v28, v27
	v_div_scale_f32 v28, vcc, 1.0, v25, 1.0
	v_mul_f32_e32 v29, v28, v27
	v_fma_f32 v30, -v26, v29, v28
	v_fmac_f32_e32 v29, v30, v27
	v_fma_f32 v26, -v26, v29, v28
	v_div_fmas_f32 v26, v26, v27, v29
	v_div_fixup_f32 v25, v26, v25, 1.0
	v_cvt_pk_bf16_f32 v25, v25, s0
	ds_write_b16 v24, v25 offset:34176
	v_add_f32_e32 v25, v13, v86
	v_mul_f32_e32 v25, 0xbfb8aa3b, v25
	v_exp_f32_e32 v25, v25
	s_nop 0
	v_add_f32_e32 v25, 1.0, v25
	v_div_scale_f32 v26, s[4:5], v25, v25, 1.0
	v_rcp_f32_e32 v27, v26
	s_nop 0
	v_fma_f32 v28, -v26, v27, 1.0
	v_fmac_f32_e32 v27, v28, v27
	v_div_scale_f32 v28, vcc, 1.0, v25, 1.0
	v_mul_f32_e32 v29, v28, v27
	v_fma_f32 v30, -v26, v29, v28
	v_fmac_f32_e32 v29, v30, v27
	v_fma_f32 v26, -v26, v29, v28
	v_div_fmas_f32 v26, v26, v27, v29
	v_div_fixup_f32 v25, v26, v25, 1.0
	v_cvt_pk_bf16_f32 v25, v25, s0
	ds_write_b16 v24, v25 offset:35216
	v_add_f32_e32 v25, v14, v86
	v_mul_f32_e32 v25, 0xbfb8aa3b, v25
	v_exp_f32_e32 v25, v25
	v_add_f32_e32 v23, v15, v86
	v_mul_f32_e32 v23, 0xbfb8aa3b, v23
	v_exp_f32_e32 v23, v23
	v_add_f32_e32 v25, 1.0, v25
	v_div_scale_f32 v26, s[4:5], v25, v25, 1.0
	v_rcp_f32_e32 v27, v26
	v_add_f32_e32 v23, 1.0, v23
	v_fma_f32 v28, -v26, v27, 1.0
	v_fmac_f32_e32 v27, v28, v27
	v_div_scale_f32 v28, vcc, 1.0, v25, 1.0
	v_mul_f32_e32 v29, v28, v27
	v_fma_f32 v30, -v26, v29, v28
	v_fmac_f32_e32 v29, v30, v27
	v_fma_f32 v26, -v26, v29, v28
	v_div_fmas_f32 v26, v26, v27, v29
	v_div_fixup_f32 v25, v26, v25, 1.0
	v_cvt_pk_bf16_f32 v25, v25, s0
	ds_write_b16 v24, v25 offset:36256
	v_div_scale_f32 v25, s[4:5], v23, v23, 1.0
	v_rcp_f32_e32 v26, v25
	s_nop 0
	v_fma_f32 v27, -v25, v26, 1.0
	v_fmac_f32_e32 v26, v27, v26
	v_div_scale_f32 v27, vcc, 1.0, v23, 1.0
	v_mul_f32_e32 v28, v27, v26
	v_fma_f32 v29, -v25, v28, v27
	v_fmac_f32_e32 v28, v29, v26
	v_fma_f32 v25, -v25, v28, v27
	v_div_fmas_f32 v25, v25, v26, v28
	v_div_fixup_f32 v23, v25, v23, 1.0
	v_cvt_pk_bf16_f32 v23, v23, s0
	ds_write_b16 v24, v23 offset:37296
	s_cbranch_execnz .LBB0_516
.LBB0_520:
	v_readlane_b32 s12, v255, 29
	v_lshlrev_b64 v[18:19], 2, v[18:19]
	v_readlane_b32 s16, v255, 33
	v_readlane_b32 s17, v255, 34
	v_readlane_b32 s13, v255, 30
	v_readlane_b32 s14, v255, 31
	v_lshl_add_u64 v[24:25], s[16:17], 0, v[18:19]
	v_lshl_add_u64 v[18:19], v[16:17], 0, v[18:19]
	v_readlane_b32 s15, v255, 32
	v_readlane_b32 s18, v255, 35
	v_readlane_b32 s19, v255, 36
	v_readlane_b32 s20, v255, 37
	v_readlane_b32 s21, v255, 38
	v_readlane_b32 s22, v255, 39
	v_readlane_b32 s23, v255, 40
	v_readlane_b32 s24, v255, 41
	v_readlane_b32 s25, v255, 42
	v_readlane_b32 s26, v255, 43
	v_readlane_b32 s27, v255, 44
	s_waitcnt vmcnt(0)
	v_add_f32_e32 v0, v0, v86
	v_mul_f32_e32 v0, 0xbfb8aa3b, v0
	v_exp_f32_e32 v0, v0
	s_nop 0
	v_add_f32_e32 v0, 1.0, v0
	v_div_scale_f32 v24, s[4:5], v0, v0, 1.0
	v_rcp_f32_e32 v25, v24
	s_nop 0
	v_fma_f32 v26, -v24, v25, 1.0
	v_fmac_f32_e32 v25, v26, v25
	v_div_scale_f32 v26, vcc, 1.0, v0, 1.0
	v_mul_f32_e32 v27, v26, v25
	v_fma_f32 v28, -v24, v27, v26
	v_fmac_f32_e32 v27, v28, v25
	v_fma_f32 v24, -v24, v27, v26
	v_div_fmas_f32 v24, v24, v25, v27
	v_div_fixup_f32 v0, v24, v0, 1.0
	v_mul_f32_e32 v0, 0xbf1b4598, v0
	v_mul_f32_e32 v0, 0x3fb8aa3b, v0
	v_exp_f32_e32 v0, v0
	global_store_dword v[18:19], v0, off nt
	v_add_f32_e32 v0, v1, v86
	v_mul_f32_e32 v0, 0xbfb8aa3b, v0
	v_exp_f32_e32 v0, v0
	s_nop 0
	v_add_f32_e32 v0, 1.0, v0
	v_div_scale_f32 v1, s[4:5], v0, v0, 1.0
	v_rcp_f32_e32 v24, v1
	s_nop 0
	v_fma_f32 v25, -v1, v24, 1.0
	v_fmac_f32_e32 v24, v25, v24
	v_div_scale_f32 v25, vcc, 1.0, v0, 1.0
	v_mul_f32_e32 v26, v25, v24
	v_fma_f32 v27, -v1, v26, v25
	v_fmac_f32_e32 v26, v27, v24
	v_fma_f32 v1, -v1, v26, v25
	v_div_fmas_f32 v1, v1, v24, v26
	v_div_fixup_f32 v0, v1, v0, 1.0
	v_mul_f32_e32 v0, 0xbf1b4598, v0
	v_mul_f32_e32 v0, 0x3fb8aa3b, v0
	v_exp_f32_e32 v0, v0
	global_store_dword v[18:19], v0, off offset:2048 nt
	v_add_f32_e32 v0, v2, v86
	v_mul_f32_e32 v0, 0xbfb8aa3b, v0
	v_exp_f32_e32 v0, v0
	s_nop 0
	v_add_f32_e32 v0, 1.0, v0
	v_div_scale_f32 v1, s[4:5], v0, v0, 1.0
	v_rcp_f32_e32 v2, v1
	s_movk_i32 s4, 0x1000
	v_fma_f32 v24, -v1, v2, 1.0
	v_fmac_f32_e32 v2, v24, v2
	v_div_scale_f32 v24, vcc, 1.0, v0, 1.0
	v_mul_f32_e32 v25, v24, v2
	v_fma_f32 v26, -v1, v25, v24
	v_fmac_f32_e32 v25, v26, v2
	v_fma_f32 v1, -v1, v25, v24
	v_div_fmas_f32 v1, v1, v2, v25
	v_div_fixup_f32 v0, v1, v0, 1.0
	v_mul_f32_e32 v0, 0xbf1b4598, v0
	v_mul_f32_e32 v0, 0x3fb8aa3b, v0
	v_exp_f32_e32 v2, v0
	v_add_co_u32_e32 v0, vcc, s4, v18
	s_nop 1
	v_addc_co_u32_e32 v1, vcc, 0, v19, vcc
	global_store_dword v[0:1], v2, off nt
	v_add_f32_e32 v2, v3, v86
	v_mul_f32_e32 v2, 0xbfb8aa3b, v2
	v_exp_f32_e32 v2, v2
	s_nop 0
	v_add_f32_e32 v2, 1.0, v2
	v_div_scale_f32 v3, s[4:5], v2, v2, 1.0
	v_rcp_f32_e32 v24, v3
	s_nop 0
	v_fma_f32 v25, -v3, v24, 1.0
	v_fmac_f32_e32 v24, v25, v24
	v_div_scale_f32 v25, vcc, 1.0, v2, 1.0
	v_mul_f32_e32 v26, v25, v24
	v_fma_f32 v27, -v3, v26, v25
	v_fmac_f32_e32 v26, v27, v24
	v_fma_f32 v3, -v3, v26, v25
	v_div_fmas_f32 v3, v3, v24, v26
	v_div_fixup_f32 v2, v3, v2, 1.0
	v_mul_f32_e32 v2, 0xbf1b4598, v2
	v_mul_f32_e32 v2, 0x3fb8aa3b, v2
	v_exp_f32_e32 v2, v2
	global_store_dword v[0:1], v2, off offset:2048 nt
	v_add_f32_e32 v0, v4, v86
	v_mul_f32_e32 v0, 0xbfb8aa3b, v0
	v_exp_f32_e32 v0, v0
	s_nop 0
	v_add_f32_e32 v0, 1.0, v0
	v_div_scale_f32 v1, s[4:5], v0, v0, 1.0
	v_rcp_f32_e32 v2, v1
	s_movk_i32 s4, 0x4000
	v_fma_f32 v3, -v1, v2, 1.0
	v_fmac_f32_e32 v2, v3, v2
	v_div_scale_f32 v3, vcc, 1.0, v0, 1.0
	v_mul_f32_e32 v4, v3, v2
	v_fma_f32 v24, -v1, v4, v3
	v_fmac_f32_e32 v4, v24, v2
	v_fma_f32 v1, -v1, v4, v3
	v_div_fmas_f32 v1, v1, v2, v4
	v_div_fixup_f32 v0, v1, v0, 1.0
	v_mul_f32_e32 v0, 0xbf1b4598, v0
	v_mul_f32_e32 v0, 0x3fb8aa3b, v0
	v_exp_f32_e32 v4, v0
	v_add_co_u32_e32 v0, vcc, s4, v18
	s_movk_i32 s4, 0x5000
	s_nop 0
	v_addc_co_u32_e32 v1, vcc, 0, v19, vcc
	v_add_co_u32_e32 v2, vcc, s4, v18
	s_nop 1
	v_addc_co_u32_e32 v3, vcc, 0, v19, vcc
	global_store_dword v[2:3], v4, off offset:-4096 nt
	v_add_f32_e32 v4, v5, v86
	v_mul_f32_e32 v4, 0xbfb8aa3b, v4
	v_exp_f32_e32 v4, v4
	s_nop 0
	v_add_f32_e32 v4, 1.0, v4
	v_div_scale_f32 v5, s[4:5], v4, v4, 1.0
	v_rcp_f32_e32 v24, v5
	s_nop 0
	v_fma_f32 v25, -v5, v24, 1.0
	v_fmac_f32_e32 v24, v25, v24
	v_div_scale_f32 v25, vcc, 1.0, v4, 1.0
	v_mul_f32_e32 v26, v25, v24
	v_fma_f32 v27, -v5, v26, v25
	v_fmac_f32_e32 v26, v27, v24
	v_fma_f32 v5, -v5, v26, v25
	v_div_fmas_f32 v5, v5, v24, v26
	v_div_fixup_f32 v4, v5, v4, 1.0
	v_mul_f32_e32 v4, 0xbf1b4598, v4
	v_mul_f32_e32 v4, 0x3fb8aa3b, v4
	v_exp_f32_e32 v4, v4
	global_store_dword v[0:1], v4, off offset:2048 nt
	v_add_f32_e32 v0, v6, v86
	v_mul_f32_e32 v0, 0xbfb8aa3b, v0
	v_exp_f32_e32 v0, v0
	s_nop 0
	v_add_f32_e32 v0, 1.0, v0
	v_div_scale_f32 v1, s[4:5], v0, v0, 1.0
	v_rcp_f32_e32 v4, v1
	s_nop 0
	v_fma_f32 v5, -v1, v4, 1.0
	v_fmac_f32_e32 v4, v5, v4
	v_div_scale_f32 v5, vcc, 1.0, v0, 1.0
	v_mul_f32_e32 v6, v5, v4
	v_fma_f32 v24, -v1, v6, v5
	v_fmac_f32_e32 v6, v24, v4
	v_fma_f32 v1, -v1, v6, v5
	v_div_fmas_f32 v1, v1, v4, v6
	v_div_fixup_f32 v0, v1, v0, 1.0
	v_mul_f32_e32 v0, 0xbf1b4598, v0
	v_mul_f32_e32 v0, 0x3fb8aa3b, v0
	v_exp_f32_e32 v0, v0
	global_store_dword v[2:3], v0, off nt
	v_add_f32_e32 v0, v7, v86
	v_mul_f32_e32 v0, 0xbfb8aa3b, v0
	v_exp_f32_e32 v0, v0
	s_nop 0
	v_add_f32_e32 v0, 1.0, v0
	v_div_scale_f32 v1, s[4:5], v0, v0, 1.0
	v_rcp_f32_e32 v4, v1
	s_nop 0
	v_fma_f32 v5, -v1, v4, 1.0
	v_fmac_f32_e32 v4, v5, v4
	v_div_scale_f32 v5, vcc, 1.0, v0, 1.0
	v_mul_f32_e32 v6, v5, v4
	v_fma_f32 v7, -v1, v6, v5
	v_fmac_f32_e32 v6, v7, v4
	v_fma_f32 v1, -v1, v6, v5
	v_div_fmas_f32 v1, v1, v4, v6
	v_div_fixup_f32 v0, v1, v0, 1.0
	v_mul_f32_e32 v0, 0xbf1b4598, v0
	v_mul_f32_e32 v0, 0x3fb8aa3b, v0
	v_exp_f32_e32 v0, v0
	global_store_dword v[2:3], v0, off offset:2048 nt
	v_add_f32_e32 v0, v8, v86
	v_mul_f32_e32 v0, 0xbfb8aa3b, v0
	v_exp_f32_e32 v0, v0
	s_nop 0
	v_add_f32_e32 v0, 1.0, v0
	v_div_scale_f32 v1, s[4:5], v0, v0, 1.0
	v_rcp_f32_e32 v2, v1
	s_mov_b32 s4, 0x8000
	v_fma_f32 v3, -v1, v2, 1.0
	v_fmac_f32_e32 v2, v3, v2
	v_div_scale_f32 v3, vcc, 1.0, v0, 1.0
	v_mul_f32_e32 v4, v3, v2
	v_fma_f32 v5, -v1, v4, v3
	v_fmac_f32_e32 v4, v5, v2
	v_fma_f32 v1, -v1, v4, v3
	v_div_fmas_f32 v1, v1, v2, v4
	v_div_fixup_f32 v0, v1, v0, 1.0
	v_mul_f32_e32 v0, 0xbf1b4598, v0
	v_mul_f32_e32 v0, 0x3fb8aa3b, v0
	v_exp_f32_e32 v4, v0
	v_add_co_u32_e32 v0, vcc, s4, v18
	s_mov_b32 s4, 0x9000
	s_nop 0
	v_addc_co_u32_e32 v1, vcc, 0, v19, vcc
	v_add_co_u32_e32 v2, vcc, s4, v18
	s_nop 1
	v_addc_co_u32_e32 v3, vcc, 0, v19, vcc
	global_store_dword v[2:3], v4, off offset:-4096 nt
	v_add_f32_e32 v4, v9, v86
	v_mul_f32_e32 v4, 0xbfb8aa3b, v4
	v_exp_f32_e32 v4, v4
	s_nop 0
	v_add_f32_e32 v4, 1.0, v4
	v_div_scale_f32 v5, s[4:5], v4, v4, 1.0
	v_rcp_f32_e32 v6, v5
	s_nop 0
	v_fma_f32 v7, -v5, v6, 1.0
	v_fmac_f32_e32 v6, v7, v6
	v_div_scale_f32 v7, vcc, 1.0, v4, 1.0
	v_mul_f32_e32 v8, v7, v6
	v_fma_f32 v9, -v5, v8, v7
	v_fmac_f32_e32 v8, v9, v6
	v_fma_f32 v5, -v5, v8, v7
	v_div_fmas_f32 v5, v5, v6, v8
	v_div_fixup_f32 v4, v5, v4, 1.0
	v_mul_f32_e32 v4, 0xbf1b4598, v4
	v_mul_f32_e32 v4, 0x3fb8aa3b, v4
	v_exp_f32_e32 v4, v4
	global_store_dword v[0:1], v4, off offset:2048 nt
	v_add_f32_e32 v0, v10, v86
	v_mul_f32_e32 v0, 0xbfb8aa3b, v0
	v_exp_f32_e32 v0, v0
	s_nop 0
	v_add_f32_e32 v0, 1.0, v0
	v_div_scale_f32 v1, s[4:5], v0, v0, 1.0
	v_rcp_f32_e32 v4, v1
	s_nop 0
	v_fma_f32 v5, -v1, v4, 1.0
	v_fmac_f32_e32 v4, v5, v4
	v_div_scale_f32 v5, vcc, 1.0, v0, 1.0
	v_mul_f32_e32 v6, v5, v4
	v_fma_f32 v7, -v1, v6, v5
	v_fmac_f32_e32 v6, v7, v4
	v_fma_f32 v1, -v1, v6, v5
	v_div_fmas_f32 v1, v1, v4, v6
	v_div_fixup_f32 v0, v1, v0, 1.0
	v_mul_f32_e32 v0, 0xbf1b4598, v0
	v_mul_f32_e32 v0, 0x3fb8aa3b, v0
	v_exp_f32_e32 v0, v0
	global_store_dword v[2:3], v0, off nt
	v_add_f32_e32 v0, v11, v86
	v_mul_f32_e32 v0, 0xbfb8aa3b, v0
	v_exp_f32_e32 v0, v0
	s_nop 0
	v_add_f32_e32 v0, 1.0, v0
	v_div_scale_f32 v1, s[4:5], v0, v0, 1.0
	v_rcp_f32_e32 v4, v1
	s_nop 0
	v_fma_f32 v5, -v1, v4, 1.0
	v_fmac_f32_e32 v4, v5, v4
	v_div_scale_f32 v5, vcc, 1.0, v0, 1.0
	v_mul_f32_e32 v6, v5, v4
	v_fma_f32 v7, -v1, v6, v5
	v_fmac_f32_e32 v6, v7, v4
	v_fma_f32 v1, -v1, v6, v5
	v_div_fmas_f32 v1, v1, v4, v6
	v_div_fixup_f32 v0, v1, v0, 1.0
	v_mul_f32_e32 v0, 0xbf1b4598, v0
	v_mul_f32_e32 v0, 0x3fb8aa3b, v0
	v_exp_f32_e32 v0, v0
	global_store_dword v[2:3], v0, off offset:2048 nt
	v_add_f32_e32 v0, v12, v86
	v_mul_f32_e32 v0, 0xbfb8aa3b, v0
	v_exp_f32_e32 v0, v0
	s_nop 0
	v_add_f32_e32 v0, 1.0, v0
	v_div_scale_f32 v1, s[4:5], v0, v0, 1.0
	v_rcp_f32_e32 v2, v1
	s_mov_b32 s4, 0xc000
	v_fma_f32 v3, -v1, v2, 1.0
	v_fmac_f32_e32 v2, v3, v2
	v_div_scale_f32 v3, vcc, 1.0, v0, 1.0
	v_mul_f32_e32 v4, v3, v2
	v_fma_f32 v5, -v1, v4, v3
	v_fmac_f32_e32 v4, v5, v2
	v_fma_f32 v1, -v1, v4, v3
	v_div_fmas_f32 v1, v1, v2, v4
	v_div_fixup_f32 v0, v1, v0, 1.0
	v_mul_f32_e32 v0, 0xbf1b4598, v0
	v_mul_f32_e32 v0, 0x3fb8aa3b, v0
	v_exp_f32_e32 v4, v0
	v_add_co_u32_e32 v0, vcc, s4, v18
	s_mov_b32 s4, 0xd000
	s_nop 0
	v_addc_co_u32_e32 v1, vcc, 0, v19, vcc
	v_add_co_u32_e32 v2, vcc, s4, v18
	s_nop 1
	v_addc_co_u32_e32 v3, vcc, 0, v19, vcc
	global_store_dword v[2:3], v4, off offset:-4096 nt
	v_add_f32_e32 v4, v13, v86
	v_mul_f32_e32 v4, 0xbfb8aa3b, v4
	v_exp_f32_e32 v4, v4
	s_nop 0
	v_add_f32_e32 v4, 1.0, v4
	v_div_scale_f32 v5, s[4:5], v4, v4, 1.0
	v_rcp_f32_e32 v6, v5
	s_nop 0
	v_fma_f32 v7, -v5, v6, 1.0
	v_fmac_f32_e32 v6, v7, v6
	v_div_scale_f32 v7, vcc, 1.0, v4, 1.0
	v_mul_f32_e32 v8, v7, v6
	v_fma_f32 v9, -v5, v8, v7
	v_fmac_f32_e32 v8, v9, v6
	v_fma_f32 v5, -v5, v8, v7
	v_div_fmas_f32 v5, v5, v6, v8
	v_div_fixup_f32 v4, v5, v4, 1.0
	v_mul_f32_e32 v4, 0xbf1b4598, v4
	v_mul_f32_e32 v4, 0x3fb8aa3b, v4
	v_exp_f32_e32 v4, v4
	global_store_dword v[0:1], v4, off offset:2048 nt
	v_add_f32_e32 v0, v14, v86
	v_mul_f32_e32 v0, 0xbfb8aa3b, v0
	v_exp_f32_e32 v0, v0
	s_nop 0
	v_add_f32_e32 v0, 1.0, v0
	v_div_scale_f32 v1, s[4:5], v0, v0, 1.0
	v_rcp_f32_e32 v4, v1
	s_nop 0
	v_fma_f32 v5, -v1, v4, 1.0
	v_fmac_f32_e32 v4, v5, v4
	v_div_scale_f32 v5, vcc, 1.0, v0, 1.0
	v_mul_f32_e32 v6, v5, v4
	v_fma_f32 v7, -v1, v6, v5
	v_fmac_f32_e32 v6, v7, v4
	v_fma_f32 v1, -v1, v6, v5
	v_div_fmas_f32 v1, v1, v4, v6
	v_div_fixup_f32 v0, v1, v0, 1.0
	v_mul_f32_e32 v0, 0xbf1b4598, v0
	v_mul_f32_e32 v0, 0x3fb8aa3b, v0
	v_exp_f32_e32 v0, v0
	global_store_dword v[2:3], v0, off nt
	v_add_f32_e32 v0, v15, v86
	v_mul_f32_e32 v0, 0xbfb8aa3b, v0
	v_exp_f32_e32 v0, v0
	s_nop 0
	v_add_f32_e32 v0, 1.0, v0
	v_div_scale_f32 v1, s[4:5], v0, v0, 1.0
	v_rcp_f32_e32 v4, v1
	s_nop 0
	v_fma_f32 v5, -v1, v4, 1.0
	v_fmac_f32_e32 v4, v5, v4
	v_div_scale_f32 v5, vcc, 1.0, v0, 1.0
	v_mul_f32_e32 v6, v5, v4
	v_fma_f32 v7, -v1, v6, v5
	v_fmac_f32_e32 v6, v7, v4
	v_fma_f32 v1, -v1, v6, v5
	v_div_fmas_f32 v1, v1, v4, v6
	v_div_fixup_f32 v0, v1, v0, 1.0
	v_mul_f32_e32 v0, 0xbf1b4598, v0
	v_mul_f32_e32 v0, 0x3fb8aa3b, v0
	v_exp_f32_e32 v0, v0
	global_store_dword v[2:3], v0, off offset:2048 nt
	s_branch .LBB0_516

.LBB0_1191:
	ds_read_b128 v[32:35], v76 offset:512
	ds_read_b128 v[36:39], v76 offset:256
	ds_read_b128 v[40:43], v76 offset:0
	ds_read_b32 v44, v97 offset:1280
	ds_read_b128 v[140:143], v76 offset:768
	ds_read_b128 v[144:147], v76 offset:1024
	ds_read_b128 v[108:111], v76 offset:1856
	ds_read_b128 v[112:115], v76 offset:1600
	ds_read_b128 v[116:119], v76 offset:1344
	ds_read_b32 v120, v97 offset:2624
	ds_read_b128 v[56:59], v76 offset:2112
	ds_read_b128 v[64:67], v76 offset:2368
	s_waitcnt lgkmcnt(11)
	v_pk_mul_f32 v[122:123], v[60:61], v[32:33]
	v_pk_fma_f32 v[122:123], v[52:53], v[34:35], v[122:123]
	s_waitcnt lgkmcnt(8)
	v_add_f32_e32 v49, v122, v123
	v_pk_mul_f32 v[122:123], v[36:37], v[44:45] op_sel_hi:[1,0]
	v_pk_mul_f32 v[138:139], v[38:39], v[44:45] op_sel_hi:[1,0]
	v_add_f32_dpp v49, v49, v49 quad_perm:[1,0,3,2] row_mask:0xf bank_mask:0xf bound_ctrl:1
	v_pk_fma_f32 v[60:61], v[60:61], v[40:41], v[122:123]
	v_pk_fma_f32 v[52:53], v[52:53], v[42:43], v[138:139]
	v_add_f32_dpp v49, v49, v49 quad_perm:[2,3,0,1] row_mask:0xf bank_mask:0xf bound_ctrl:1
	ds_read_b128 v[124:127], v76 offset:3200
	ds_read_b128 v[128:131], v76 offset:2944
	v_add_f32_dpp v49, v49, v49 row_half_mirror row_mask:0xf bank_mask:0xf bound_ctrl:1
	ds_read_b128 v[132:135], v76 offset:2688
	ds_read_b32 v136, v97 offset:3968
	v_add_f32_dpp v48, v49, v49 row_ror:8 row_mask:0xf bank_mask:0xf bound_ctrl:1
	s_waitcnt lgkmcnt(6)
	v_pk_fma_f32 v[60:61], v[140:141], v[48:49], v[60:61] op_sel_hi:[1,0,1] neg_lo:[0,1,0] neg_hi:[0,1,0]
	v_pk_fma_f32 v[52:53], v[142:143], v[48:49], v[52:53] op_sel_hi:[1,0,1] neg_lo:[0,1,0] neg_hi:[0,1,0]
	v_pk_mul_f32 v[122:123], v[60:61], v[108:109]
	v_pk_fma_f32 v[122:123], v[52:53], v[110:111], v[122:123]
	v_add_f32_e32 v49, v122, v123
	v_pk_mul_f32 v[122:123], v[60:61], v[144:145]
	v_pk_fma_f32 v[122:123], v[52:53], v[146:147], v[122:123]
	ds_read_b128 v[140:143], v76 offset:3456
	v_add_f32_dpp v49, v49, v49 quad_perm:[1,0,3,2] row_mask:0xf bank_mask:0xf bound_ctrl:1
	v_add_f32_e32 v90, v122, v123
	v_pk_mul_f32 v[122:123], v[112:113], v[120:121] op_sel_hi:[1,0]
	ds_read_b128 v[144:147], v76 offset:3712
	v_add_f32_dpp v49, v49, v49 quad_perm:[2,3,0,1] row_mask:0xf bank_mask:0xf bound_ctrl:1
	v_pk_mul_f32 v[138:139], v[114:115], v[120:121] op_sel_hi:[1,0]
	v_pk_fma_f32 v[60:61], v[60:61], v[116:117], v[122:123]
	ds_read_b128 v[32:35], v76 offset:4544
	v_add_f32_dpp v49, v49, v49 row_half_mirror row_mask:0xf bank_mask:0xf bound_ctrl:1
	v_pk_fma_f32 v[52:53], v[52:53], v[118:119], v[138:139]
	ds_read_b128 v[36:39], v76 offset:4288
	ds_read_b128 v[40:43], v76 offset:4032
	ds_read_b32 v44, v97 offset:5312
	v_add_f32_dpp v48, v49, v49 row_ror:8 row_mask:0xf bank_mask:0xf bound_ctrl:1
	s_waitcnt lgkmcnt(6)
	v_pk_fma_f32 v[60:61], v[56:57], v[48:49], v[60:61] op_sel_hi:[1,0,1] neg_lo:[0,1,0] neg_hi:[0,1,0]
	v_pk_fma_f32 v[52:53], v[58:59], v[48:49], v[52:53] op_sel_hi:[1,0,1] neg_lo:[0,1,0] neg_hi:[0,1,0]
	v_pk_mul_f32 v[122:123], v[60:61], v[124:125]
	v_pk_fma_f32 v[122:123], v[52:53], v[126:127], v[122:123]
	v_add_f32_e32 v49, v122, v123
	v_pk_mul_f32 v[122:123], v[60:61], v[64:65]
	v_pk_fma_f32 v[122:123], v[52:53], v[66:67], v[122:123]
	ds_read_b128 v[56:59], v76 offset:4800
	v_add_f32_dpp v49, v49, v49 quad_perm:[1,0,3,2] row_mask:0xf bank_mask:0xf bound_ctrl:1
	v_add_f32_e32 v91, v122, v123
	v_pk_mul_f32 v[122:123], v[128:129], v[136:137] op_sel_hi:[1,0]
	ds_read_b128 v[64:67], v76 offset:5056
	v_add_f32_dpp v49, v49, v49 quad_perm:[2,3,0,1] row_mask:0xf bank_mask:0xf bound_ctrl:1
	v_pk_mul_f32 v[138:139], v[130:131], v[136:137] op_sel_hi:[1,0]
	v_pk_fma_f32 v[60:61], v[60:61], v[132:133], v[122:123]
	ds_read_b128 v[108:111], v76 offset:5888
	v_add_f32_dpp v49, v49, v49 row_half_mirror row_mask:0xf bank_mask:0xf bound_ctrl:1
	v_pk_fma_f32 v[52:53], v[52:53], v[134:135], v[138:139]
	ds_read_b128 v[112:115], v76 offset:5632
	ds_read_b128 v[116:119], v76 offset:5376
	ds_read_b32 v120, v97 offset:6656
	v_add_f32_dpp v48, v49, v49 row_ror:8 row_mask:0xf bank_mask:0xf bound_ctrl:1
	s_waitcnt lgkmcnt(6)
	v_pk_fma_f32 v[60:61], v[140:141], v[48:49], v[60:61] op_sel_hi:[1,0,1] neg_lo:[0,1,0] neg_hi:[0,1,0]
	v_pk_fma_f32 v[52:53], v[142:143], v[48:49], v[52:53] op_sel_hi:[1,0,1] neg_lo:[0,1,0] neg_hi:[0,1,0]
	v_pk_mul_f32 v[122:123], v[60:61], v[32:33]
	v_pk_fma_f32 v[122:123], v[52:53], v[34:35], v[122:123]
	v_add_f32_e32 v49, v122, v123
	v_pk_mul_f32 v[122:123], v[60:61], v[144:145]
	v_pk_fma_f32 v[122:123], v[52:53], v[146:147], v[122:123]
	ds_read_b128 v[140:143], v76 offset:6144
	v_add_f32_dpp v49, v49, v49 quad_perm:[1,0,3,2] row_mask:0xf bank_mask:0xf bound_ctrl:1
	v_add_f32_e32 v92, v122, v123
	v_pk_mul_f32 v[122:123], v[36:37], v[44:45] op_sel_hi:[1,0]
	ds_read_b128 v[144:147], v76 offset:6400
	v_add_f32_dpp v49, v49, v49 quad_perm:[2,3,0,1] row_mask:0xf bank_mask:0xf bound_ctrl:1
	v_pk_mul_f32 v[138:139], v[38:39], v[44:45] op_sel_hi:[1,0]
	v_pk_fma_f32 v[60:61], v[60:61], v[40:41], v[122:123]
	ds_read_b128 v[124:127], v76 offset:7232
	v_add_f32_dpp v49, v49, v49 row_half_mirror row_mask:0xf bank_mask:0xf bound_ctrl:1
	v_pk_fma_f32 v[52:53], v[52:53], v[42:43], v[138:139]
	ds_read_b128 v[128:131], v76 offset:6976
	ds_read_b128 v[132:135], v76 offset:6720
	ds_read_b32 v136, v97 offset:8000
	v_add_f32_dpp v48, v49, v49 row_ror:8 row_mask:0xf bank_mask:0xf bound_ctrl:1
	s_waitcnt lgkmcnt(6)
	v_pk_fma_f32 v[60:61], v[56:57], v[48:49], v[60:61] op_sel_hi:[1,0,1] neg_lo:[0,1,0] neg_hi:[0,1,0]
	v_pk_fma_f32 v[52:53], v[58:59], v[48:49], v[52:53] op_sel_hi:[1,0,1] neg_lo:[0,1,0] neg_hi:[0,1,0]
	v_pk_mul_f32 v[122:123], v[60:61], v[108:109]
	v_pk_fma_f32 v[122:123], v[52:53], v[110:111], v[122:123]
	v_add_f32_e32 v49, v122, v123
	v_pk_mul_f32 v[122:123], v[60:61], v[64:65]
	v_pk_fma_f32 v[122:123], v[52:53], v[66:67], v[122:123]
	ds_read_b128 v[56:59], v76 offset:7488
	v_add_f32_dpp v49, v49, v49 quad_perm:[1,0,3,2] row_mask:0xf bank_mask:0xf bound_ctrl:1
	v_add_f32_e32 v93, v122, v123
	v_pk_mul_f32 v[122:123], v[112:113], v[120:121] op_sel_hi:[1,0]
	ds_read_b128 v[64:67], v76 offset:7744
	v_add_f32_dpp v49, v49, v49 quad_perm:[2,3,0,1] row_mask:0xf bank_mask:0xf bound_ctrl:1
	v_pk_mul_f32 v[138:139], v[114:115], v[120:121] op_sel_hi:[1,0]
	v_pk_fma_f32 v[60:61], v[60:61], v[116:117], v[122:123]
	ds_read_b128 v[32:35], v76 offset:8576
	v_add_f32_dpp v49, v49, v49 row_half_mirror row_mask:0xf bank_mask:0xf bound_ctrl:1
	v_pk_fma_f32 v[52:53], v[52:53], v[118:119], v[138:139]
	ds_read_b128 v[36:39], v76 offset:8320
	ds_read_b128 v[40:43], v76 offset:8064
	ds_read_b32 v44, v97 offset:9344
	v_add_f32_dpp v48, v49, v49 row_ror:8 row_mask:0xf bank_mask:0xf bound_ctrl:1
	s_waitcnt lgkmcnt(6)
	v_pk_fma_f32 v[60:61], v[140:141], v[48:49], v[60:61] op_sel_hi:[1,0,1] neg_lo:[0,1,0] neg_hi:[0,1,0]
	v_pk_fma_f32 v[52:53], v[142:143], v[48:49], v[52:53] op_sel_hi:[1,0,1] neg_lo:[0,1,0] neg_hi:[0,1,0]
	v_pk_mul_f32 v[122:123], v[60:61], v[124:125]
	v_pk_fma_f32 v[122:123], v[52:53], v[126:127], v[122:123]
	v_add_f32_e32 v49, v122, v123
	v_pk_mul_f32 v[122:123], v[60:61], v[144:145]
	v_pk_fma_f32 v[122:123], v[52:53], v[146:147], v[122:123]
	ds_read_b128 v[140:143], v76 offset:8832
	v_add_f32_dpp v49, v49, v49 quad_perm:[1,0,3,2] row_mask:0xf bank_mask:0xf bound_ctrl:1
	v_add_f32_e32 v45, v122, v123
	v_pk_mul_f32 v[122:123], v[128:129], v[136:137] op_sel_hi:[1,0]
	ds_read_b128 v[144:147], v76 offset:9088
	v_add_f32_dpp v49, v49, v49 quad_perm:[2,3,0,1] row_mask:0xf bank_mask:0xf bound_ctrl:1
	v_pk_mul_f32 v[138:139], v[130:131], v[136:137] op_sel_hi:[1,0]
	v_pk_fma_f32 v[60:61], v[60:61], v[132:133], v[122:123]
	ds_read_b128 v[108:111], v76 offset:9920
	v_add_f32_dpp v49, v49, v49 row_half_mirror row_mask:0xf bank_mask:0xf bound_ctrl:1
	v_pk_fma_f32 v[52:53], v[52:53], v[134:135], v[138:139]
	ds_read_b128 v[112:115], v76 offset:9664
	ds_read_b128 v[116:119], v76 offset:9408
	ds_read_b32 v120, v97 offset:10688
	v_add_f32_dpp v48, v49, v49 row_ror:8 row_mask:0xf bank_mask:0xf bound_ctrl:1
	s_waitcnt lgkmcnt(6)
	v_pk_fma_f32 v[60:61], v[56:57], v[48:49], v[60:61] op_sel_hi:[1,0,1] neg_lo:[0,1,0] neg_hi:[0,1,0]
	v_pk_fma_f32 v[52:53], v[58:59], v[48:49], v[52:53] op_sel_hi:[1,0,1] neg_lo:[0,1,0] neg_hi:[0,1,0]
	v_pk_mul_f32 v[122:123], v[60:61], v[32:33]
	v_pk_fma_f32 v[122:123], v[52:53], v[34:35], v[122:123]
	v_add_f32_e32 v49, v122, v123
	v_pk_mul_f32 v[122:123], v[60:61], v[64:65]
	v_pk_fma_f32 v[122:123], v[52:53], v[66:67], v[122:123]
	ds_read_b128 v[56:59], v76 offset:10176
	v_add_f32_dpp v49, v49, v49 quad_perm:[1,0,3,2] row_mask:0xf bank_mask:0xf bound_ctrl:1
	v_add_f32_e32 v46, v122, v123
	v_pk_mul_f32 v[122:123], v[36:37], v[44:45] op_sel_hi:[1,0]
	ds_read_b128 v[64:67], v76 offset:10432
	v_add_f32_dpp v49, v49, v49 quad_perm:[2,3,0,1] row_mask:0xf bank_mask:0xf bound_ctrl:1
	v_pk_mul_f32 v[138:139], v[38:39], v[44:45] op_sel_hi:[1,0]
	v_pk_fma_f32 v[60:61], v[60:61], v[40:41], v[122:123]
	ds_read_b128 v[124:127], v76 offset:11264
	v_add_f32_dpp v49, v49, v49 row_half_mirror row_mask:0xf bank_mask:0xf bound_ctrl:1
	v_pk_fma_f32 v[52:53], v[52:53], v[42:43], v[138:139]
	ds_read_b128 v[128:131], v76 offset:11008
	ds_read_b128 v[132:135], v76 offset:10752
	ds_read_b32 v136, v97 offset:12032
	v_add_f32_dpp v48, v49, v49 row_ror:8 row_mask:0xf bank_mask:0xf bound_ctrl:1
	s_waitcnt lgkmcnt(6)
	v_pk_fma_f32 v[60:61], v[140:141], v[48:49], v[60:61] op_sel_hi:[1,0,1] neg_lo:[0,1,0] neg_hi:[0,1,0]
	v_pk_fma_f32 v[52:53], v[142:143], v[48:49], v[52:53] op_sel_hi:[1,0,1] neg_lo:[0,1,0] neg_hi:[0,1,0]
	v_pk_mul_f32 v[122:123], v[60:61], v[108:109]
	v_pk_fma_f32 v[122:123], v[52:53], v[110:111], v[122:123]
	v_add_f32_e32 v49, v122, v123
	v_pk_mul_f32 v[122:123], v[60:61], v[144:145]
	v_pk_fma_f32 v[122:123], v[52:53], v[146:147], v[122:123]
	ds_read_b128 v[140:143], v76 offset:11520
	v_add_f32_dpp v49, v49, v49 quad_perm:[1,0,3,2] row_mask:0xf bank_mask:0xf bound_ctrl:1
	v_add_f32_e32 v47, v122, v123
	v_pk_mul_f32 v[122:123], v[112:113], v[120:121] op_sel_hi:[1,0]
	ds_read_b128 v[144:147], v76 offset:11776
	v_add_f32_dpp v49, v49, v49 quad_perm:[2,3,0,1] row_mask:0xf bank_mask:0xf bound_ctrl:1
	v_pk_mul_f32 v[138:139], v[114:115], v[120:121] op_sel_hi:[1,0]
	v_pk_fma_f32 v[60:61], v[60:61], v[116:117], v[122:123]
	ds_read_b128 v[32:35], v76 offset:12608
	v_add_f32_dpp v49, v49, v49 row_half_mirror row_mask:0xf bank_mask:0xf bound_ctrl:1
	v_pk_fma_f32 v[52:53], v[52:53], v[118:119], v[138:139]
	ds_read_b128 v[36:39], v76 offset:12352
	ds_read_b128 v[40:43], v76 offset:12096
	ds_read_b32 v44, v97 offset:13376
	v_add_f32_dpp v48, v49, v49 row_ror:8 row_mask:0xf bank_mask:0xf bound_ctrl:1
	s_waitcnt lgkmcnt(6)
	v_pk_fma_f32 v[60:61], v[56:57], v[48:49], v[60:61] op_sel_hi:[1,0,1] neg_lo:[0,1,0] neg_hi:[0,1,0]
	v_pk_fma_f32 v[52:53], v[58:59], v[48:49], v[52:53] op_sel_hi:[1,0,1] neg_lo:[0,1,0] neg_hi:[0,1,0]
	v_pk_mul_f32 v[122:123], v[60:61], v[124:125]
	v_pk_fma_f32 v[122:123], v[52:53], v[126:127], v[122:123]
	v_add_f32_e32 v49, v122, v123
	v_pk_mul_f32 v[122:123], v[60:61], v[64:65]
	v_pk_fma_f32 v[122:123], v[52:53], v[66:67], v[122:123]
	ds_read_b128 v[56:59], v76 offset:12864
	v_add_f32_dpp v49, v49, v49 quad_perm:[1,0,3,2] row_mask:0xf bank_mask:0xf bound_ctrl:1
	v_add_f32_e32 v50, v122, v123
	v_pk_mul_f32 v[122:123], v[128:129], v[136:137] op_sel_hi:[1,0]
	ds_read_b128 v[64:67], v76 offset:13120
	v_add_f32_dpp v49, v49, v49 quad_perm:[2,3,0,1] row_mask:0xf bank_mask:0xf bound_ctrl:1
	v_pk_mul_f32 v[138:139], v[130:131], v[136:137] op_sel_hi:[1,0]
	v_pk_fma_f32 v[60:61], v[60:61], v[132:133], v[122:123]
	ds_read_b128 v[108:111], v76 offset:13952
	v_add_f32_dpp v49, v49, v49 row_half_mirror row_mask:0xf bank_mask:0xf bound_ctrl:1
	v_pk_fma_f32 v[52:53], v[52:53], v[134:135], v[138:139]
	ds_read_b128 v[112:115], v76 offset:13696
	ds_read_b128 v[116:119], v76 offset:13440
	ds_read_b32 v120, v97 offset:14720
	v_add_f32_dpp v48, v49, v49 row_ror:8 row_mask:0xf bank_mask:0xf bound_ctrl:1
	s_waitcnt lgkmcnt(6)
	v_pk_fma_f32 v[60:61], v[140:141], v[48:49], v[60:61] op_sel_hi:[1,0,1] neg_lo:[0,1,0] neg_hi:[0,1,0]
	v_pk_fma_f32 v[52:53], v[142:143], v[48:49], v[52:53] op_sel_hi:[1,0,1] neg_lo:[0,1,0] neg_hi:[0,1,0]
	v_pk_mul_f32 v[122:123], v[60:61], v[32:33]
	v_pk_fma_f32 v[122:123], v[52:53], v[34:35], v[122:123]
	v_add_f32_e32 v49, v122, v123
	v_pk_mul_f32 v[122:123], v[60:61], v[144:145]
	v_pk_fma_f32 v[122:123], v[52:53], v[146:147], v[122:123]
	ds_read_b128 v[140:143], v76 offset:14208
	v_add_f32_dpp v49, v49, v49 quad_perm:[1,0,3,2] row_mask:0xf bank_mask:0xf bound_ctrl:1
	v_add_f32_e32 v51, v122, v123
	v_pk_mul_f32 v[122:123], v[36:37], v[44:45] op_sel_hi:[1,0]
	ds_read_b128 v[144:147], v76 offset:14464
	v_add_f32_dpp v49, v49, v49 quad_perm:[2,3,0,1] row_mask:0xf bank_mask:0xf bound_ctrl:1
	v_pk_mul_f32 v[138:139], v[38:39], v[44:45] op_sel_hi:[1,0]
	v_pk_fma_f32 v[60:61], v[60:61], v[40:41], v[122:123]
	ds_read_b128 v[124:127], v76 offset:15296
	v_add_f32_dpp v49, v49, v49 row_half_mirror row_mask:0xf bank_mask:0xf bound_ctrl:1
	v_pk_fma_f32 v[52:53], v[52:53], v[42:43], v[138:139]
	ds_read_b128 v[128:131], v76 offset:15040
	ds_read_b128 v[132:135], v76 offset:14784
	ds_read_b32 v136, v97 offset:16064
	v_add_f32_dpp v48, v49, v49 row_ror:8 row_mask:0xf bank_mask:0xf bound_ctrl:1
	s_waitcnt lgkmcnt(6)
	v_pk_fma_f32 v[60:61], v[56:57], v[48:49], v[60:61] op_sel_hi:[1,0,1] neg_lo:[0,1,0] neg_hi:[0,1,0]
	v_pk_fma_f32 v[52:53], v[58:59], v[48:49], v[52:53] op_sel_hi:[1,0,1] neg_lo:[0,1,0] neg_hi:[0,1,0]
	v_pk_mul_f32 v[122:123], v[60:61], v[108:109]
	v_pk_fma_f32 v[122:123], v[52:53], v[110:111], v[122:123]
	v_add_f32_e32 v49, v122, v123
	v_pk_mul_f32 v[122:123], v[60:61], v[64:65]
	v_pk_fma_f32 v[122:123], v[52:53], v[66:67], v[122:123]
	ds_read_b128 v[56:59], v76 offset:15552
	v_add_f32_dpp v49, v49, v49 quad_perm:[1,0,3,2] row_mask:0xf bank_mask:0xf bound_ctrl:1
	v_add_f32_e32 v54, v122, v123
	v_pk_mul_f32 v[122:123], v[112:113], v[120:121] op_sel_hi:[1,0]
	ds_read_b128 v[64:67], v76 offset:15808
	v_add_f32_dpp v49, v49, v49 quad_perm:[2,3,0,1] row_mask:0xf bank_mask:0xf bound_ctrl:1
	v_pk_mul_f32 v[138:139], v[114:115], v[120:121] op_sel_hi:[1,0]
	v_pk_fma_f32 v[60:61], v[60:61], v[116:117], v[122:123]
	ds_read_b128 v[32:35], v76 offset:16640
	v_add_f32_dpp v49, v49, v49 row_half_mirror row_mask:0xf bank_mask:0xf bound_ctrl:1
	v_pk_fma_f32 v[52:53], v[52:53], v[118:119], v[138:139]
	ds_read_b128 v[36:39], v76 offset:16384
	ds_read_b128 v[40:43], v76 offset:16128
	ds_read_b32 v44, v97 offset:17408
	v_add_f32_dpp v48, v49, v49 row_ror:8 row_mask:0xf bank_mask:0xf bound_ctrl:1
	s_waitcnt lgkmcnt(6)
	v_pk_fma_f32 v[60:61], v[140:141], v[48:49], v[60:61] op_sel_hi:[1,0,1] neg_lo:[0,1,0] neg_hi:[0,1,0]
	v_pk_fma_f32 v[52:53], v[142:143], v[48:49], v[52:53] op_sel_hi:[1,0,1] neg_lo:[0,1,0] neg_hi:[0,1,0]
	v_pk_mul_f32 v[122:123], v[60:61], v[124:125]
	v_pk_fma_f32 v[122:123], v[52:53], v[126:127], v[122:123]
	v_add_f32_e32 v49, v122, v123
	v_pk_mul_f32 v[122:123], v[60:61], v[144:145]
	v_pk_fma_f32 v[122:123], v[52:53], v[146:147], v[122:123]
	ds_read_b128 v[140:143], v76 offset:16896
	v_add_f32_dpp v49, v49, v49 quad_perm:[1,0,3,2] row_mask:0xf bank_mask:0xf bound_ctrl:1
	v_add_f32_e32 v55, v122, v123
	v_pk_mul_f32 v[122:123], v[128:129], v[136:137] op_sel_hi:[1,0]
	ds_read_b128 v[144:147], v76 offset:17152
	v_add_f32_dpp v49, v49, v49 quad_perm:[2,3,0,1] row_mask:0xf bank_mask:0xf bound_ctrl:1
	v_pk_mul_f32 v[138:139], v[130:131], v[136:137] op_sel_hi:[1,0]
	v_pk_fma_f32 v[60:61], v[60:61], v[132:133], v[122:123]
	ds_read_b128 v[108:111], v76 offset:17984
	v_add_f32_dpp v49, v49, v49 row_half_mirror row_mask:0xf bank_mask:0xf bound_ctrl:1
	v_pk_fma_f32 v[52:53], v[52:53], v[134:135], v[138:139]
	ds_read_b128 v[112:115], v76 offset:17728
	ds_read_b128 v[116:119], v76 offset:17472
	ds_read_b32 v120, v97 offset:18752
	v_add_f32_dpp v48, v49, v49 row_ror:8 row_mask:0xf bank_mask:0xf bound_ctrl:1
	s_waitcnt lgkmcnt(6)
	v_pk_fma_f32 v[60:61], v[56:57], v[48:49], v[60:61] op_sel_hi:[1,0,1] neg_lo:[0,1,0] neg_hi:[0,1,0]
	v_pk_fma_f32 v[52:53], v[58:59], v[48:49], v[52:53] op_sel_hi:[1,0,1] neg_lo:[0,1,0] neg_hi:[0,1,0]
	v_pk_mul_f32 v[122:123], v[60:61], v[32:33]
	v_pk_fma_f32 v[122:123], v[52:53], v[34:35], v[122:123]
	v_add_f32_e32 v49, v122, v123
	v_pk_mul_f32 v[122:123], v[60:61], v[64:65]
	v_pk_fma_f32 v[122:123], v[52:53], v[66:67], v[122:123]
	ds_read_b128 v[56:59], v76 offset:18240
	v_add_f32_dpp v49, v49, v49 quad_perm:[1,0,3,2] row_mask:0xf bank_mask:0xf bound_ctrl:1
	v_add_f32_e32 v62, v122, v123
	v_pk_mul_f32 v[122:123], v[36:37], v[44:45] op_sel_hi:[1,0]
	ds_read_b128 v[64:67], v76 offset:18496
	v_add_f32_dpp v49, v49, v49 quad_perm:[2,3,0,1] row_mask:0xf bank_mask:0xf bound_ctrl:1
	v_pk_mul_f32 v[138:139], v[38:39], v[44:45] op_sel_hi:[1,0]
	v_pk_fma_f32 v[60:61], v[60:61], v[40:41], v[122:123]
	ds_read_b128 v[124:127], v76 offset:19328
	v_add_f32_dpp v49, v49, v49 row_half_mirror row_mask:0xf bank_mask:0xf bound_ctrl:1
	v_pk_fma_f32 v[52:53], v[52:53], v[42:43], v[138:139]
	ds_read_b128 v[128:131], v76 offset:19072
	ds_read_b128 v[132:135], v76 offset:18816
	ds_read_b32 v136, v97 offset:20096
	v_add_f32_dpp v48, v49, v49 row_ror:8 row_mask:0xf bank_mask:0xf bound_ctrl:1
	s_waitcnt lgkmcnt(6)
	v_pk_fma_f32 v[60:61], v[140:141], v[48:49], v[60:61] op_sel_hi:[1,0,1] neg_lo:[0,1,0] neg_hi:[0,1,0]
	v_pk_fma_f32 v[52:53], v[142:143], v[48:49], v[52:53] op_sel_hi:[1,0,1] neg_lo:[0,1,0] neg_hi:[0,1,0]
	v_pk_mul_f32 v[122:123], v[60:61], v[108:109]
	v_pk_fma_f32 v[122:123], v[52:53], v[110:111], v[122:123]
	v_add_f32_e32 v49, v122, v123
	v_pk_mul_f32 v[122:123], v[60:61], v[144:145]
	v_pk_fma_f32 v[122:123], v[52:53], v[146:147], v[122:123]
	ds_read_b128 v[140:143], v76 offset:19584
	v_add_f32_dpp v49, v49, v49 quad_perm:[1,0,3,2] row_mask:0xf bank_mask:0xf bound_ctrl:1
	v_add_f32_e32 v63, v122, v123
	v_pk_mul_f32 v[122:123], v[112:113], v[120:121] op_sel_hi:[1,0]
	ds_read_b128 v[144:147], v76 offset:19840
	v_add_f32_dpp v49, v49, v49 quad_perm:[2,3,0,1] row_mask:0xf bank_mask:0xf bound_ctrl:1
	v_pk_mul_f32 v[138:139], v[114:115], v[120:121] op_sel_hi:[1,0]
	v_pk_fma_f32 v[60:61], v[60:61], v[116:117], v[122:123]
	ds_read_b128 v[32:35], v76 offset:20672
	v_add_f32_dpp v49, v49, v49 row_half_mirror row_mask:0xf bank_mask:0xf bound_ctrl:1
	v_pk_fma_f32 v[52:53], v[52:53], v[118:119], v[138:139]
	ds_read_b128 v[36:39], v76 offset:20416
	ds_read_b128 v[40:43], v76 offset:20160
	ds_read_b32 v44, v97 offset:21440
	v_add_f32_dpp v48, v49, v49 row_ror:8 row_mask:0xf bank_mask:0xf bound_ctrl:1
	s_waitcnt lgkmcnt(6)
	v_pk_fma_f32 v[60:61], v[56:57], v[48:49], v[60:61] op_sel_hi:[1,0,1] neg_lo:[0,1,0] neg_hi:[0,1,0]
	v_pk_fma_f32 v[52:53], v[58:59], v[48:49], v[52:53] op_sel_hi:[1,0,1] neg_lo:[0,1,0] neg_hi:[0,1,0]
	v_pk_mul_f32 v[122:123], v[60:61], v[124:125]
	v_pk_fma_f32 v[122:123], v[52:53], v[126:127], v[122:123]
	v_add_f32_e32 v49, v122, v123
	v_pk_mul_f32 v[122:123], v[60:61], v[64:65]
	v_pk_fma_f32 v[122:123], v[52:53], v[66:67], v[122:123]
	ds_read_b128 v[56:59], v76 offset:20928
	v_add_f32_dpp v49, v49, v49 quad_perm:[1,0,3,2] row_mask:0xf bank_mask:0xf bound_ctrl:1
	v_add_f32_e32 v68, v122, v123
	v_pk_mul_f32 v[122:123], v[128:129], v[136:137] op_sel_hi:[1,0]
	ds_read_b128 v[64:67], v76 offset:21184
	v_add_f32_dpp v49, v49, v49 quad_perm:[2,3,0,1] row_mask:0xf bank_mask:0xf bound_ctrl:1
	v_pk_mul_f32 v[138:139], v[130:131], v[136:137] op_sel_hi:[1,0]
	v_pk_fma_f32 v[60:61], v[60:61], v[132:133], v[122:123]
	v_add_f32_dpp v49, v49, v49 row_half_mirror row_mask:0xf bank_mask:0xf bound_ctrl:1
	v_pk_fma_f32 v[52:53], v[52:53], v[134:135], v[138:139]
	s_nop 0
	v_add_f32_dpp v48, v49, v49 row_ror:8 row_mask:0xf bank_mask:0xf bound_ctrl:1
	s_waitcnt lgkmcnt(2)
	v_pk_fma_f32 v[60:61], v[140:141], v[48:49], v[60:61] op_sel_hi:[1,0,1] neg_lo:[0,1,0] neg_hi:[0,1,0]
	v_pk_fma_f32 v[52:53], v[142:143], v[48:49], v[52:53] op_sel_hi:[1,0,1] neg_lo:[0,1,0] neg_hi:[0,1,0]
	v_pk_mul_f32 v[122:123], v[60:61], v[32:33]
	v_pk_fma_f32 v[122:123], v[52:53], v[34:35], v[122:123]
	v_add_f32_e32 v49, v122, v123
	v_pk_mul_f32 v[122:123], v[60:61], v[144:145]
	v_pk_fma_f32 v[122:123], v[52:53], v[146:147], v[122:123]
	v_add_f32_dpp v49, v49, v49 quad_perm:[1,0,3,2] row_mask:0xf bank_mask:0xf bound_ctrl:1
	v_add_f32_e32 v88, v122, v123
	v_pk_mul_f32 v[122:123], v[36:37], v[44:45] op_sel_hi:[1,0]
	v_add_f32_dpp v49, v49, v49 quad_perm:[2,3,0,1] row_mask:0xf bank_mask:0xf bound_ctrl:1
	v_pk_mul_f32 v[138:139], v[38:39], v[44:45] op_sel_hi:[1,0]
	v_pk_fma_f32 v[60:61], v[60:61], v[40:41], v[122:123]
	v_add_f32_dpp v49, v49, v49 row_half_mirror row_mask:0xf bank_mask:0xf bound_ctrl:1
	v_pk_fma_f32 v[52:53], v[52:53], v[42:43], v[138:139]
	s_nop 0
	v_add_f32_dpp v48, v49, v49 row_ror:8 row_mask:0xf bank_mask:0xf bound_ctrl:1
	s_waitcnt lgkmcnt(0)
	v_pk_fma_f32 v[60:61], v[56:57], v[48:49], v[60:61] op_sel_hi:[1,0,1] neg_lo:[0,1,0] neg_hi:[0,1,0]
	v_pk_fma_f32 v[52:53], v[58:59], v[48:49], v[52:53] op_sel_hi:[1,0,1] neg_lo:[0,1,0] neg_hi:[0,1,0]
	v_pk_mul_f32 v[122:123], v[60:61], v[64:65]
	v_pk_fma_f32 v[122:123], v[52:53], v[66:67], v[122:123]
	v_add_f32_e32 v107, v122, v123
	v_add_f32_dpp v90, v90, v90 row_ror:8 row_mask:0xf bank_mask:0x3
	v_add_f32_dpp v91, v91, v91 row_ror:8 row_mask:0xf bank_mask:0x3
	v_add_f32_dpp v92, v92, v92 row_ror:8 row_mask:0xf bank_mask:0x3
	v_add_f32_dpp v93, v93, v93 row_ror:8 row_mask:0xf bank_mask:0x3
	v_add_f32_dpp v45, v45, v45 row_ror:8 row_mask:0xf bank_mask:0x3
	v_add_f32_dpp v46, v46, v46 row_ror:8 row_mask:0xf bank_mask:0x3
	v_add_f32_dpp v47, v47, v47 row_ror:8 row_mask:0xf bank_mask:0x3
	v_add_f32_dpp v50, v50, v50 row_ror:8 row_mask:0xf bank_mask:0x3
	v_add_f32_dpp v90, v51, v51 row_ror:8 row_mask:0xf bank_mask:0xc
	v_add_f32_dpp v91, v54, v54 row_ror:8 row_mask:0xf bank_mask:0xc
	v_add_f32_dpp v92, v55, v55 row_ror:8 row_mask:0xf bank_mask:0xc
	v_add_f32_dpp v93, v62, v62 row_ror:8 row_mask:0xf bank_mask:0xc
	v_add_f32_dpp v45, v63, v63 row_ror:8 row_mask:0xf bank_mask:0xc
	v_add_f32_dpp v46, v68, v68 row_ror:8 row_mask:0xf bank_mask:0xc
	v_add_f32_dpp v47, v88, v88 row_ror:8 row_mask:0xf bank_mask:0xc
	v_add_f32_dpp v50, v107, v107 row_ror:8 row_mask:0xf bank_mask:0xc
	v_add_f32_dpp v90, v90, v90 row_ror:12 row_mask:0xf bank_mask:0x5
	v_add_f32_dpp v91, v91, v91 row_ror:12 row_mask:0xf bank_mask:0x5
	v_add_f32_dpp v92, v92, v92 row_ror:12 row_mask:0xf bank_mask:0x5
	v_add_f32_dpp v93, v93, v93 row_ror:12 row_mask:0xf bank_mask:0x5
	v_add_f32_dpp v90, v45, v45 row_ror:4 row_mask:0xf bank_mask:0xa
	v_add_f32_dpp v91, v46, v46 row_ror:4 row_mask:0xf bank_mask:0xa
	v_add_f32_dpp v92, v47, v47 row_ror:4 row_mask:0xf bank_mask:0xa
	v_add_f32_dpp v93, v50, v50 row_ror:4 row_mask:0xf bank_mask:0xa
	s_mov_b32 vcc_lo, 0xcccccccc
	s_mov_b32 vcc_hi, 0xcccccccc
	v_cndmask_b32_e32 v51, v92, v90, vcc
	v_cndmask_b32_e32 v54, v93, v91, vcc
	v_cndmask_b32_e32 v55, v90, v92, vcc
	v_cndmask_b32_e32 v62, v91, v93, vcc
	v_add_f32_dpp v90, v51, v55 quad_perm:[2,3,0,1] row_mask:0xf bank_mask:0xf
	v_add_f32_dpp v91, v54, v62 quad_perm:[2,3,0,1] row_mask:0xf bank_mask:0xf
	s_mov_b32 vcc_lo, 0xaaaaaaaa
	s_mov_b32 vcc_hi, 0xaaaaaaaa
	v_cndmask_b32_e32 v51, v91, v90, vcc
	v_cndmask_b32_e32 v55, v90, v91, vcc
	s_nop 1
	v_add_f32_dpp v109, v51, v55 quad_perm:[1,0,3,2] row_mask:0xf bank_mask:0xf
.LBB0_1195:
	s_cmp_eq_u32 s20, 0
	s_cselect_b64 vcc, -1, 0
	s_or_b64 vcc, vcc, s[10:11]
	s_cbranch_vccnz .Lscan_wsb_all
	s_cmp_lg_u64 s[4:5], 0
	s_cbranch_scc1 .Lscan_wsb_w0
	s_waitcnt vmcnt(4)
	s_branch .Lscan_wsb_done
.Lscan_wsb_w0:
	s_waitcnt vmcnt(5)
	s_branch .Lscan_wsb_done

.Lscan_wsb_done:
	v_lshlrev_b32_e32 v32, 16, v16
	v_and_b32_e32 v33, 0xffff0000, v16
	v_lshlrev_b32_e32 v34, 16, v17
	v_and_b32_e32 v35, 0xffff0000, v17
	ds_write_b32 v98, v109 offset:43008
	v_lshlrev_b32_e32 v36, 16, v18
	v_and_b32_e32 v37, 0xffff0000, v18
	v_lshlrev_b32_e32 v38, 16, v19
	v_and_b32_e32 v39, 0xffff0000, v19
	ds_write_b128 v94, v[32:35] offset:21504
	ds_write_b128 v94, v[36:39] offset:21520
	v_lshlrev_b32_e32 v32, 16, v20
	v_and_b32_e32 v33, 0xffff0000, v20
	v_lshlrev_b32_e32 v34, 16, v21
	v_and_b32_e32 v35, 0xffff0000, v21
	v_lshlrev_b32_e32 v36, 16, v22
	v_and_b32_e32 v37, 0xffff0000, v22
	v_lshlrev_b32_e32 v38, 16, v23
	v_and_b32_e32 v39, 0xffff0000, v23
	ds_write_b128 v95, v[32:35] offset:21504
	ds_write_b128 v95, v[36:39] offset:21520
	ds_write_b128 v96, v[24:27] offset:21504
	s_and_saveexec_b64 s[16:17], s[4:5]
	s_cbranch_execz .LBB0_1197
	v_lshlrev_b32_e32 v32, 16, v28
	v_and_b32_e32 v33, 0xffff0000, v28
	v_lshlrev_b32_e32 v34, 16, v29
	v_and_b32_e32 v35, 0xffff0000, v29
	v_lshlrev_b32_e32 v36, 16, v30
	v_and_b32_e32 v37, 0xffff0000, v30
	v_lshlrev_b32_e32 v38, 16, v31
	v_and_b32_e32 v39, 0xffff0000, v31
	ds_write_b128 v100, v[32:35] offset:22784
	ds_write_b128 v100, v[36:39] offset:22800

.LBB0_1201:
	ds_read_b128 v[32:35], v76 offset:22016
	ds_read_b128 v[36:39], v76 offset:21760
	ds_read_b128 v[40:43], v76 offset:21504
	ds_read_b32 v44, v97 offset:22784
	ds_read_b128 v[140:143], v76 offset:22272
	ds_read_b128 v[144:147], v76 offset:22528
	ds_read_b128 v[108:111], v76 offset:23360
	ds_read_b128 v[112:115], v76 offset:23104
	ds_read_b128 v[116:119], v76 offset:22848
	ds_read_b32 v120, v97 offset:24128
	ds_read_b128 v[56:59], v76 offset:23616
	ds_read_b128 v[64:67], v76 offset:23872
	s_waitcnt lgkmcnt(11)
	v_pk_mul_f32 v[122:123], v[60:61], v[32:33]
	v_pk_fma_f32 v[122:123], v[52:53], v[34:35], v[122:123]
	s_waitcnt lgkmcnt(8)
	v_add_f32_e32 v49, v122, v123
	v_pk_mul_f32 v[122:123], v[36:37], v[44:45] op_sel_hi:[1,0]
	v_pk_mul_f32 v[138:139], v[38:39], v[44:45] op_sel_hi:[1,0]
	v_add_f32_dpp v49, v49, v49 quad_perm:[1,0,3,2] row_mask:0xf bank_mask:0xf bound_ctrl:1
	v_pk_fma_f32 v[60:61], v[60:61], v[40:41], v[122:123]
	v_pk_fma_f32 v[52:53], v[52:53], v[42:43], v[138:139]
	v_add_f32_dpp v49, v49, v49 quad_perm:[2,3,0,1] row_mask:0xf bank_mask:0xf bound_ctrl:1
	ds_read_b128 v[124:127], v76 offset:24704
	ds_read_b128 v[128:131], v76 offset:24448
	v_add_f32_dpp v49, v49, v49 row_half_mirror row_mask:0xf bank_mask:0xf bound_ctrl:1
	ds_read_b128 v[132:135], v76 offset:24192
	ds_read_b32 v136, v97 offset:25472
	v_add_f32_dpp v48, v49, v49 row_ror:8 row_mask:0xf bank_mask:0xf bound_ctrl:1
	s_waitcnt lgkmcnt(6)
	v_pk_fma_f32 v[60:61], v[140:141], v[48:49], v[60:61] op_sel_hi:[1,0,1] neg_lo:[0,1,0] neg_hi:[0,1,0]
	v_pk_fma_f32 v[52:53], v[142:143], v[48:49], v[52:53] op_sel_hi:[1,0,1] neg_lo:[0,1,0] neg_hi:[0,1,0]
	v_pk_mul_f32 v[122:123], v[60:61], v[108:109]
	v_pk_fma_f32 v[122:123], v[52:53], v[110:111], v[122:123]
	v_add_f32_e32 v49, v122, v123
	v_pk_mul_f32 v[122:123], v[60:61], v[144:145]
	v_pk_fma_f32 v[122:123], v[52:53], v[146:147], v[122:123]
	ds_read_b128 v[140:143], v76 offset:24960
	v_add_f32_dpp v49, v49, v49 quad_perm:[1,0,3,2] row_mask:0xf bank_mask:0xf bound_ctrl:1
	v_add_f32_e32 v90, v122, v123
	v_pk_mul_f32 v[122:123], v[112:113], v[120:121] op_sel_hi:[1,0]
	ds_read_b128 v[144:147], v76 offset:25216
	v_add_f32_dpp v49, v49, v49 quad_perm:[2,3,0,1] row_mask:0xf bank_mask:0xf bound_ctrl:1
	v_pk_mul_f32 v[138:139], v[114:115], v[120:121] op_sel_hi:[1,0]
	v_pk_fma_f32 v[60:61], v[60:61], v[116:117], v[122:123]
	ds_read_b128 v[32:35], v76 offset:26048
	v_add_f32_dpp v49, v49, v49 row_half_mirror row_mask:0xf bank_mask:0xf bound_ctrl:1
	v_pk_fma_f32 v[52:53], v[52:53], v[118:119], v[138:139]
	ds_read_b128 v[36:39], v76 offset:25792
	ds_read_b128 v[40:43], v76 offset:25536
	ds_read_b32 v44, v97 offset:26816
	v_add_f32_dpp v48, v49, v49 row_ror:8 row_mask:0xf bank_mask:0xf bound_ctrl:1
	s_waitcnt lgkmcnt(6)
	v_pk_fma_f32 v[60:61], v[56:57], v[48:49], v[60:61] op_sel_hi:[1,0,1] neg_lo:[0,1,0] neg_hi:[0,1,0]
	v_pk_fma_f32 v[52:53], v[58:59], v[48:49], v[52:53] op_sel_hi:[1,0,1] neg_lo:[0,1,0] neg_hi:[0,1,0]
	v_pk_mul_f32 v[122:123], v[60:61], v[124:125]
	v_pk_fma_f32 v[122:123], v[52:53], v[126:127], v[122:123]
	v_add_f32_e32 v49, v122, v123
	v_pk_mul_f32 v[122:123], v[60:61], v[64:65]
	v_pk_fma_f32 v[122:123], v[52:53], v[66:67], v[122:123]
	ds_read_b128 v[56:59], v76 offset:26304
	v_add_f32_dpp v49, v49, v49 quad_perm:[1,0,3,2] row_mask:0xf bank_mask:0xf bound_ctrl:1
	v_add_f32_e32 v91, v122, v123
	v_pk_mul_f32 v[122:123], v[128:129], v[136:137] op_sel_hi:[1,0]
	ds_read_b128 v[64:67], v76 offset:26560
	v_add_f32_dpp v49, v49, v49 quad_perm:[2,3,0,1] row_mask:0xf bank_mask:0xf bound_ctrl:1
	v_pk_mul_f32 v[138:139], v[130:131], v[136:137] op_sel_hi:[1,0]
	v_pk_fma_f32 v[60:61], v[60:61], v[132:133], v[122:123]
	ds_read_b128 v[108:111], v76 offset:27392
	v_add_f32_dpp v49, v49, v49 row_half_mirror row_mask:0xf bank_mask:0xf bound_ctrl:1
	v_pk_fma_f32 v[52:53], v[52:53], v[134:135], v[138:139]
	ds_read_b128 v[112:115], v76 offset:27136
	ds_read_b128 v[116:119], v76 offset:26880
	ds_read_b32 v120, v97 offset:28160
	v_add_f32_dpp v48, v49, v49 row_ror:8 row_mask:0xf bank_mask:0xf bound_ctrl:1
	s_waitcnt lgkmcnt(6)
	v_pk_fma_f32 v[60:61], v[140:141], v[48:49], v[60:61] op_sel_hi:[1,0,1] neg_lo:[0,1,0] neg_hi:[0,1,0]
	v_pk_fma_f32 v[52:53], v[142:143], v[48:49], v[52:53] op_sel_hi:[1,0,1] neg_lo:[0,1,0] neg_hi:[0,1,0]
	v_pk_mul_f32 v[122:123], v[60:61], v[32:33]
	v_pk_fma_f32 v[122:123], v[52:53], v[34:35], v[122:123]
	v_add_f32_e32 v49, v122, v123
	v_pk_mul_f32 v[122:123], v[60:61], v[144:145]
	v_pk_fma_f32 v[122:123], v[52:53], v[146:147], v[122:123]
	ds_read_b128 v[140:143], v76 offset:27648
	v_add_f32_dpp v49, v49, v49 quad_perm:[1,0,3,2] row_mask:0xf bank_mask:0xf bound_ctrl:1
	v_add_f32_e32 v92, v122, v123
	v_pk_mul_f32 v[122:123], v[36:37], v[44:45] op_sel_hi:[1,0]
	ds_read_b128 v[144:147], v76 offset:27904
	v_add_f32_dpp v49, v49, v49 quad_perm:[2,3,0,1] row_mask:0xf bank_mask:0xf bound_ctrl:1
	v_pk_mul_f32 v[138:139], v[38:39], v[44:45] op_sel_hi:[1,0]
	v_pk_fma_f32 v[60:61], v[60:61], v[40:41], v[122:123]
	ds_read_b128 v[124:127], v76 offset:28736
	v_add_f32_dpp v49, v49, v49 row_half_mirror row_mask:0xf bank_mask:0xf bound_ctrl:1
	v_pk_fma_f32 v[52:53], v[52:53], v[42:43], v[138:139]
	ds_read_b128 v[128:131], v76 offset:28480
	ds_read_b128 v[132:135], v76 offset:28224
	ds_read_b32 v136, v97 offset:29504
	v_add_f32_dpp v48, v49, v49 row_ror:8 row_mask:0xf bank_mask:0xf bound_ctrl:1
	s_waitcnt lgkmcnt(6)
	v_pk_fma_f32 v[60:61], v[56:57], v[48:49], v[60:61] op_sel_hi:[1,0,1] neg_lo:[0,1,0] neg_hi:[0,1,0]
	v_pk_fma_f32 v[52:53], v[58:59], v[48:49], v[52:53] op_sel_hi:[1,0,1] neg_lo:[0,1,0] neg_hi:[0,1,0]
	v_pk_mul_f32 v[122:123], v[60:61], v[108:109]
	v_pk_fma_f32 v[122:123], v[52:53], v[110:111], v[122:123]
	v_add_f32_e32 v49, v122, v123
	v_pk_mul_f32 v[122:123], v[60:61], v[64:65]
	v_pk_fma_f32 v[122:123], v[52:53], v[66:67], v[122:123]
	ds_read_b128 v[56:59], v76 offset:28992
	v_add_f32_dpp v49, v49, v49 quad_perm:[1,0,3,2] row_mask:0xf bank_mask:0xf bound_ctrl:1
	v_add_f32_e32 v93, v122, v123
	v_pk_mul_f32 v[122:123], v[112:113], v[120:121] op_sel_hi:[1,0]
	ds_read_b128 v[64:67], v76 offset:29248
	v_add_f32_dpp v49, v49, v49 quad_perm:[2,3,0,1] row_mask:0xf bank_mask:0xf bound_ctrl:1
	v_pk_mul_f32 v[138:139], v[114:115], v[120:121] op_sel_hi:[1,0]
	v_pk_fma_f32 v[60:61], v[60:61], v[116:117], v[122:123]
	ds_read_b128 v[32:35], v76 offset:30080
	v_add_f32_dpp v49, v49, v49 row_half_mirror row_mask:0xf bank_mask:0xf bound_ctrl:1
	v_pk_fma_f32 v[52:53], v[52:53], v[118:119], v[138:139]
	ds_read_b128 v[36:39], v76 offset:29824
	ds_read_b128 v[40:43], v76 offset:29568
	ds_read_b32 v44, v97 offset:30848
	v_add_f32_dpp v48, v49, v49 row_ror:8 row_mask:0xf bank_mask:0xf bound_ctrl:1
	s_waitcnt lgkmcnt(6)
	v_pk_fma_f32 v[60:61], v[140:141], v[48:49], v[60:61] op_sel_hi:[1,0,1] neg_lo:[0,1,0] neg_hi:[0,1,0]
	v_pk_fma_f32 v[52:53], v[142:143], v[48:49], v[52:53] op_sel_hi:[1,0,1] neg_lo:[0,1,0] neg_hi:[0,1,0]
	v_pk_mul_f32 v[122:123], v[60:61], v[124:125]
	v_pk_fma_f32 v[122:123], v[52:53], v[126:127], v[122:123]
	v_add_f32_e32 v49, v122, v123
	v_pk_mul_f32 v[122:123], v[60:61], v[144:145]
	v_pk_fma_f32 v[122:123], v[52:53], v[146:147], v[122:123]
	ds_read_b128 v[140:143], v76 offset:30336
	v_add_f32_dpp v49, v49, v49 quad_perm:[1,0,3,2] row_mask:0xf bank_mask:0xf bound_ctrl:1
	v_add_f32_e32 v45, v122, v123
	v_pk_mul_f32 v[122:123], v[128:129], v[136:137] op_sel_hi:[1,0]
	ds_read_b128 v[144:147], v76 offset:30592
	v_add_f32_dpp v49, v49, v49 quad_perm:[2,3,0,1] row_mask:0xf bank_mask:0xf bound_ctrl:1
	v_pk_mul_f32 v[138:139], v[130:131], v[136:137] op_sel_hi:[1,0]
	v_pk_fma_f32 v[60:61], v[60:61], v[132:133], v[122:123]
	ds_read_b128 v[108:111], v76 offset:31424
	v_add_f32_dpp v49, v49, v49 row_half_mirror row_mask:0xf bank_mask:0xf bound_ctrl:1
	v_pk_fma_f32 v[52:53], v[52:53], v[134:135], v[138:139]
	ds_read_b128 v[112:115], v76 offset:31168
	ds_read_b128 v[116:119], v76 offset:30912
	ds_read_b32 v120, v97 offset:32192
	v_add_f32_dpp v48, v49, v49 row_ror:8 row_mask:0xf bank_mask:0xf bound_ctrl:1
	s_waitcnt lgkmcnt(6)
	v_pk_fma_f32 v[60:61], v[56:57], v[48:49], v[60:61] op_sel_hi:[1,0,1] neg_lo:[0,1,0] neg_hi:[0,1,0]
	v_pk_fma_f32 v[52:53], v[58:59], v[48:49], v[52:53] op_sel_hi:[1,0,1] neg_lo:[0,1,0] neg_hi:[0,1,0]
	v_pk_mul_f32 v[122:123], v[60:61], v[32:33]
	v_pk_fma_f32 v[122:123], v[52:53], v[34:35], v[122:123]
	v_add_f32_e32 v49, v122, v123
	v_pk_mul_f32 v[122:123], v[60:61], v[64:65]
	v_pk_fma_f32 v[122:123], v[52:53], v[66:67], v[122:123]
	ds_read_b128 v[56:59], v76 offset:31680
	v_add_f32_dpp v49, v49, v49 quad_perm:[1,0,3,2] row_mask:0xf bank_mask:0xf bound_ctrl:1
	v_add_f32_e32 v46, v122, v123
	v_pk_mul_f32 v[122:123], v[36:37], v[44:45] op_sel_hi:[1,0]
	ds_read_b128 v[64:67], v76 offset:31936
	v_add_f32_dpp v49, v49, v49 quad_perm:[2,3,0,1] row_mask:0xf bank_mask:0xf bound_ctrl:1
	v_pk_mul_f32 v[138:139], v[38:39], v[44:45] op_sel_hi:[1,0]
	v_pk_fma_f32 v[60:61], v[60:61], v[40:41], v[122:123]
	ds_read_b128 v[124:127], v76 offset:32768
	v_add_f32_dpp v49, v49, v49 row_half_mirror row_mask:0xf bank_mask:0xf bound_ctrl:1
	v_pk_fma_f32 v[52:53], v[52:53], v[42:43], v[138:139]
	ds_read_b128 v[128:131], v76 offset:32512
	ds_read_b128 v[132:135], v76 offset:32256
	ds_read_b32 v136, v97 offset:33536
	v_add_f32_dpp v48, v49, v49 row_ror:8 row_mask:0xf bank_mask:0xf bound_ctrl:1
	s_waitcnt lgkmcnt(6)
	v_pk_fma_f32 v[60:61], v[140:141], v[48:49], v[60:61] op_sel_hi:[1,0,1] neg_lo:[0,1,0] neg_hi:[0,1,0]
	v_pk_fma_f32 v[52:53], v[142:143], v[48:49], v[52:53] op_sel_hi:[1,0,1] neg_lo:[0,1,0] neg_hi:[0,1,0]
	v_pk_mul_f32 v[122:123], v[60:61], v[108:109]
	v_pk_fma_f32 v[122:123], v[52:53], v[110:111], v[122:123]
	v_add_f32_e32 v49, v122, v123
	v_pk_mul_f32 v[122:123], v[60:61], v[144:145]
	v_pk_fma_f32 v[122:123], v[52:53], v[146:147], v[122:123]
	ds_read_b128 v[140:143], v76 offset:33024
	v_add_f32_dpp v49, v49, v49 quad_perm:[1,0,3,2] row_mask:0xf bank_mask:0xf bound_ctrl:1
	v_add_f32_e32 v47, v122, v123
	v_pk_mul_f32 v[122:123], v[112:113], v[120:121] op_sel_hi:[1,0]
	ds_read_b128 v[144:147], v76 offset:33280
	v_add_f32_dpp v49, v49, v49 quad_perm:[2,3,0,1] row_mask:0xf bank_mask:0xf bound_ctrl:1
	v_pk_mul_f32 v[138:139], v[114:115], v[120:121] op_sel_hi:[1,0]
	v_pk_fma_f32 v[60:61], v[60:61], v[116:117], v[122:123]
	ds_read_b128 v[32:35], v76 offset:34112
	v_add_f32_dpp v49, v49, v49 row_half_mirror row_mask:0xf bank_mask:0xf bound_ctrl:1
	v_pk_fma_f32 v[52:53], v[52:53], v[118:119], v[138:139]
	ds_read_b128 v[36:39], v76 offset:33856
	ds_read_b128 v[40:43], v76 offset:33600
	ds_read_b32 v44, v97 offset:34880
	v_add_f32_dpp v48, v49, v49 row_ror:8 row_mask:0xf bank_mask:0xf bound_ctrl:1
	s_waitcnt lgkmcnt(6)
	v_pk_fma_f32 v[60:61], v[56:57], v[48:49], v[60:61] op_sel_hi:[1,0,1] neg_lo:[0,1,0] neg_hi:[0,1,0]
	v_pk_fma_f32 v[52:53], v[58:59], v[48:49], v[52:53] op_sel_hi:[1,0,1] neg_lo:[0,1,0] neg_hi:[0,1,0]
	v_pk_mul_f32 v[122:123], v[60:61], v[124:125]
	v_pk_fma_f32 v[122:123], v[52:53], v[126:127], v[122:123]
	v_add_f32_e32 v49, v122, v123
	v_pk_mul_f32 v[122:123], v[60:61], v[64:65]
	v_pk_fma_f32 v[122:123], v[52:53], v[66:67], v[122:123]
	ds_read_b128 v[56:59], v76 offset:34368
	v_add_f32_dpp v49, v49, v49 quad_perm:[1,0,3,2] row_mask:0xf bank_mask:0xf bound_ctrl:1
	v_add_f32_e32 v50, v122, v123
	v_pk_mul_f32 v[122:123], v[128:129], v[136:137] op_sel_hi:[1,0]
	ds_read_b128 v[64:67], v76 offset:34624
	v_add_f32_dpp v49, v49, v49 quad_perm:[2,3,0,1] row_mask:0xf bank_mask:0xf bound_ctrl:1
	v_pk_mul_f32 v[138:139], v[130:131], v[136:137] op_sel_hi:[1,0]
	v_pk_fma_f32 v[60:61], v[60:61], v[132:133], v[122:123]
	ds_read_b128 v[108:111], v76 offset:35456
	v_add_f32_dpp v49, v49, v49 row_half_mirror row_mask:0xf bank_mask:0xf bound_ctrl:1
	v_pk_fma_f32 v[52:53], v[52:53], v[134:135], v[138:139]
	ds_read_b128 v[112:115], v76 offset:35200
	ds_read_b128 v[116:119], v76 offset:34944
	ds_read_b32 v120, v97 offset:36224
	v_add_f32_dpp v48, v49, v49 row_ror:8 row_mask:0xf bank_mask:0xf bound_ctrl:1
	s_waitcnt lgkmcnt(6)
	v_pk_fma_f32 v[60:61], v[140:141], v[48:49], v[60:61] op_sel_hi:[1,0,1] neg_lo:[0,1,0] neg_hi:[0,1,0]
	v_pk_fma_f32 v[52:53], v[142:143], v[48:49], v[52:53] op_sel_hi:[1,0,1] neg_lo:[0,1,0] neg_hi:[0,1,0]
	v_pk_mul_f32 v[122:123], v[60:61], v[32:33]
	v_pk_fma_f32 v[122:123], v[52:53], v[34:35], v[122:123]
	v_add_f32_e32 v49, v122, v123
	v_pk_mul_f32 v[122:123], v[60:61], v[144:145]
	v_pk_fma_f32 v[122:123], v[52:53], v[146:147], v[122:123]
	ds_read_b128 v[140:143], v76 offset:35712
	v_add_f32_dpp v49, v49, v49 quad_perm:[1,0,3,2] row_mask:0xf bank_mask:0xf bound_ctrl:1
	v_add_f32_e32 v51, v122, v123
	v_pk_mul_f32 v[122:123], v[36:37], v[44:45] op_sel_hi:[1,0]
	ds_read_b128 v[144:147], v76 offset:35968
	v_add_f32_dpp v49, v49, v49 quad_perm:[2,3,0,1] row_mask:0xf bank_mask:0xf bound_ctrl:1
	v_pk_mul_f32 v[138:139], v[38:39], v[44:45] op_sel_hi:[1,0]
	v_pk_fma_f32 v[60:61], v[60:61], v[40:41], v[122:123]
	ds_read_b128 v[124:127], v76 offset:36800
	v_add_f32_dpp v49, v49, v49 row_half_mirror row_mask:0xf bank_mask:0xf bound_ctrl:1
	v_pk_fma_f32 v[52:53], v[52:53], v[42:43], v[138:139]
	ds_read_b128 v[128:131], v76 offset:36544
	ds_read_b128 v[132:135], v76 offset:36288
	ds_read_b32 v136, v97 offset:37568
	v_add_f32_dpp v48, v49, v49 row_ror:8 row_mask:0xf bank_mask:0xf bound_ctrl:1
	s_waitcnt lgkmcnt(6)
	v_pk_fma_f32 v[60:61], v[56:57], v[48:49], v[60:61] op_sel_hi:[1,0,1] neg_lo:[0,1,0] neg_hi:[0,1,0]
	v_pk_fma_f32 v[52:53], v[58:59], v[48:49], v[52:53] op_sel_hi:[1,0,1] neg_lo:[0,1,0] neg_hi:[0,1,0]
	v_pk_mul_f32 v[122:123], v[60:61], v[108:109]
	v_pk_fma_f32 v[122:123], v[52:53], v[110:111], v[122:123]
	v_add_f32_e32 v49, v122, v123
	v_pk_mul_f32 v[122:123], v[60:61], v[64:65]
	v_pk_fma_f32 v[122:123], v[52:53], v[66:67], v[122:123]
	ds_read_b128 v[56:59], v76 offset:37056
	v_add_f32_dpp v49, v49, v49 quad_perm:[1,0,3,2] row_mask:0xf bank_mask:0xf bound_ctrl:1
	v_add_f32_e32 v54, v122, v123
	v_pk_mul_f32 v[122:123], v[112:113], v[120:121] op_sel_hi:[1,0]
	ds_read_b128 v[64:67], v76 offset:37312
	v_add_f32_dpp v49, v49, v49 quad_perm:[2,3,0,1] row_mask:0xf bank_mask:0xf bound_ctrl:1
	v_pk_mul_f32 v[138:139], v[114:115], v[120:121] op_sel_hi:[1,0]
	v_pk_fma_f32 v[60:61], v[60:61], v[116:117], v[122:123]
	ds_read_b128 v[32:35], v76 offset:38144
	v_add_f32_dpp v49, v49, v49 row_half_mirror row_mask:0xf bank_mask:0xf bound_ctrl:1
	v_pk_fma_f32 v[52:53], v[52:53], v[118:119], v[138:139]
	ds_read_b128 v[36:39], v76 offset:37888
	ds_read_b128 v[40:43], v76 offset:37632
	ds_read_b32 v44, v97 offset:38912
	v_add_f32_dpp v48, v49, v49 row_ror:8 row_mask:0xf bank_mask:0xf bound_ctrl:1
	s_waitcnt lgkmcnt(6)
	v_pk_fma_f32 v[60:61], v[140:141], v[48:49], v[60:61] op_sel_hi:[1,0,1] neg_lo:[0,1,0] neg_hi:[0,1,0]
	v_pk_fma_f32 v[52:53], v[142:143], v[48:49], v[52:53] op_sel_hi:[1,0,1] neg_lo:[0,1,0] neg_hi:[0,1,0]
	v_pk_mul_f32 v[122:123], v[60:61], v[124:125]
	v_pk_fma_f32 v[122:123], v[52:53], v[126:127], v[122:123]
	v_add_f32_e32 v49, v122, v123
	v_pk_mul_f32 v[122:123], v[60:61], v[144:145]
	v_pk_fma_f32 v[122:123], v[52:53], v[146:147], v[122:123]
	ds_read_b128 v[140:143], v76 offset:38400
	v_add_f32_dpp v49, v49, v49 quad_perm:[1,0,3,2] row_mask:0xf bank_mask:0xf bound_ctrl:1
	v_add_f32_e32 v55, v122, v123
	v_pk_mul_f32 v[122:123], v[128:129], v[136:137] op_sel_hi:[1,0]
	ds_read_b128 v[144:147], v76 offset:38656
	v_add_f32_dpp v49, v49, v49 quad_perm:[2,3,0,1] row_mask:0xf bank_mask:0xf bound_ctrl:1
	v_pk_mul_f32 v[138:139], v[130:131], v[136:137] op_sel_hi:[1,0]
	v_pk_fma_f32 v[60:61], v[60:61], v[132:133], v[122:123]
	ds_read_b128 v[108:111], v76 offset:39488
	v_add_f32_dpp v49, v49, v49 row_half_mirror row_mask:0xf bank_mask:0xf bound_ctrl:1
	v_pk_fma_f32 v[52:53], v[52:53], v[134:135], v[138:139]
	ds_read_b128 v[112:115], v76 offset:39232
	ds_read_b128 v[116:119], v76 offset:38976
	ds_read_b32 v120, v97 offset:40256
	v_add_f32_dpp v48, v49, v49 row_ror:8 row_mask:0xf bank_mask:0xf bound_ctrl:1
	s_waitcnt lgkmcnt(6)
	v_pk_fma_f32 v[60:61], v[56:57], v[48:49], v[60:61] op_sel_hi:[1,0,1] neg_lo:[0,1,0] neg_hi:[0,1,0]
	v_pk_fma_f32 v[52:53], v[58:59], v[48:49], v[52:53] op_sel_hi:[1,0,1] neg_lo:[0,1,0] neg_hi:[0,1,0]
	v_pk_mul_f32 v[122:123], v[60:61], v[32:33]
	v_pk_fma_f32 v[122:123], v[52:53], v[34:35], v[122:123]
	v_add_f32_e32 v49, v122, v123
	v_pk_mul_f32 v[122:123], v[60:61], v[64:65]
	v_pk_fma_f32 v[122:123], v[52:53], v[66:67], v[122:123]
	ds_read_b128 v[56:59], v76 offset:39744
	v_add_f32_dpp v49, v49, v49 quad_perm:[1,0,3,2] row_mask:0xf bank_mask:0xf bound_ctrl:1
	v_add_f32_e32 v62, v122, v123
	v_pk_mul_f32 v[122:123], v[36:37], v[44:45] op_sel_hi:[1,0]
	ds_read_b128 v[64:67], v76 offset:40000
	v_add_f32_dpp v49, v49, v49 quad_perm:[2,3,0,1] row_mask:0xf bank_mask:0xf bound_ctrl:1
	v_pk_mul_f32 v[138:139], v[38:39], v[44:45] op_sel_hi:[1,0]
	v_pk_fma_f32 v[60:61], v[60:61], v[40:41], v[122:123]
	ds_read_b128 v[124:127], v76 offset:40832
	v_add_f32_dpp v49, v49, v49 row_half_mirror row_mask:0xf bank_mask:0xf bound_ctrl:1
	v_pk_fma_f32 v[52:53], v[52:53], v[42:43], v[138:139]
	ds_read_b128 v[128:131], v76 offset:40576
	ds_read_b128 v[132:135], v76 offset:40320
	ds_read_b32 v136, v97 offset:41600
	v_add_f32_dpp v48, v49, v49 row_ror:8 row_mask:0xf bank_mask:0xf bound_ctrl:1
	s_waitcnt lgkmcnt(6)
	v_pk_fma_f32 v[60:61], v[140:141], v[48:49], v[60:61] op_sel_hi:[1,0,1] neg_lo:[0,1,0] neg_hi:[0,1,0]
	v_pk_fma_f32 v[52:53], v[142:143], v[48:49], v[52:53] op_sel_hi:[1,0,1] neg_lo:[0,1,0] neg_hi:[0,1,0]
	v_pk_mul_f32 v[122:123], v[60:61], v[108:109]
	v_pk_fma_f32 v[122:123], v[52:53], v[110:111], v[122:123]
	v_add_f32_e32 v49, v122, v123
	v_pk_mul_f32 v[122:123], v[60:61], v[144:145]
	v_pk_fma_f32 v[122:123], v[52:53], v[146:147], v[122:123]
	ds_read_b128 v[140:143], v76 offset:41088
	v_add_f32_dpp v49, v49, v49 quad_perm:[1,0,3,2] row_mask:0xf bank_mask:0xf bound_ctrl:1
	v_add_f32_e32 v63, v122, v123
	v_pk_mul_f32 v[122:123], v[112:113], v[120:121] op_sel_hi:[1,0]
	ds_read_b128 v[144:147], v76 offset:41344
	v_add_f32_dpp v49, v49, v49 quad_perm:[2,3,0,1] row_mask:0xf bank_mask:0xf bound_ctrl:1
	v_pk_mul_f32 v[138:139], v[114:115], v[120:121] op_sel_hi:[1,0]
	v_pk_fma_f32 v[60:61], v[60:61], v[116:117], v[122:123]
	ds_read_b128 v[32:35], v76 offset:42176
	v_add_f32_dpp v49, v49, v49 row_half_mirror row_mask:0xf bank_mask:0xf bound_ctrl:1
	v_pk_fma_f32 v[52:53], v[52:53], v[118:119], v[138:139]
	ds_read_b128 v[36:39], v76 offset:41920
	ds_read_b128 v[40:43], v76 offset:41664
	ds_read_b32 v44, v97 offset:42944
	v_add_f32_dpp v48, v49, v49 row_ror:8 row_mask:0xf bank_mask:0xf bound_ctrl:1
	s_waitcnt lgkmcnt(6)
	v_pk_fma_f32 v[60:61], v[56:57], v[48:49], v[60:61] op_sel_hi:[1,0,1] neg_lo:[0,1,0] neg_hi:[0,1,0]
	v_pk_fma_f32 v[52:53], v[58:59], v[48:49], v[52:53] op_sel_hi:[1,0,1] neg_lo:[0,1,0] neg_hi:[0,1,0]
	v_pk_mul_f32 v[122:123], v[60:61], v[124:125]
	v_pk_fma_f32 v[122:123], v[52:53], v[126:127], v[122:123]
	v_add_f32_e32 v49, v122, v123
	v_pk_mul_f32 v[122:123], v[60:61], v[64:65]
	v_pk_fma_f32 v[122:123], v[52:53], v[66:67], v[122:123]
	ds_read_b128 v[56:59], v76 offset:42432
	v_add_f32_dpp v49, v49, v49 quad_perm:[1,0,3,2] row_mask:0xf bank_mask:0xf bound_ctrl:1
	v_add_f32_e32 v68, v122, v123
	v_pk_mul_f32 v[122:123], v[128:129], v[136:137] op_sel_hi:[1,0]
	ds_read_b128 v[64:67], v76 offset:42688
	v_add_f32_dpp v49, v49, v49 quad_perm:[2,3,0,1] row_mask:0xf bank_mask:0xf bound_ctrl:1
	v_pk_mul_f32 v[138:139], v[130:131], v[136:137] op_sel_hi:[1,0]
	v_pk_fma_f32 v[60:61], v[60:61], v[132:133], v[122:123]
	v_add_f32_dpp v49, v49, v49 row_half_mirror row_mask:0xf bank_mask:0xf bound_ctrl:1
	v_pk_fma_f32 v[52:53], v[52:53], v[134:135], v[138:139]
	s_nop 0
	v_add_f32_dpp v48, v49, v49 row_ror:8 row_mask:0xf bank_mask:0xf bound_ctrl:1
	s_waitcnt lgkmcnt(2)
	v_pk_fma_f32 v[60:61], v[140:141], v[48:49], v[60:61] op_sel_hi:[1,0,1] neg_lo:[0,1,0] neg_hi:[0,1,0]
	v_pk_fma_f32 v[52:53], v[142:143], v[48:49], v[52:53] op_sel_hi:[1,0,1] neg_lo:[0,1,0] neg_hi:[0,1,0]
	v_pk_mul_f32 v[122:123], v[60:61], v[32:33]
	v_pk_fma_f32 v[122:123], v[52:53], v[34:35], v[122:123]
	v_add_f32_e32 v49, v122, v123
	v_pk_mul_f32 v[122:123], v[60:61], v[144:145]
	v_pk_fma_f32 v[122:123], v[52:53], v[146:147], v[122:123]
	v_add_f32_dpp v49, v49, v49 quad_perm:[1,0,3,2] row_mask:0xf bank_mask:0xf bound_ctrl:1
	v_add_f32_e32 v88, v122, v123
	v_pk_mul_f32 v[122:123], v[36:37], v[44:45] op_sel_hi:[1,0]
	v_add_f32_dpp v49, v49, v49 quad_perm:[2,3,0,1] row_mask:0xf bank_mask:0xf bound_ctrl:1
	v_pk_mul_f32 v[138:139], v[38:39], v[44:45] op_sel_hi:[1,0]
	v_pk_fma_f32 v[60:61], v[60:61], v[40:41], v[122:123]
	v_add_f32_dpp v49, v49, v49 row_half_mirror row_mask:0xf bank_mask:0xf bound_ctrl:1
	v_pk_fma_f32 v[52:53], v[52:53], v[42:43], v[138:139]
	s_nop 0
	v_add_f32_dpp v48, v49, v49 row_ror:8 row_mask:0xf bank_mask:0xf bound_ctrl:1
	s_waitcnt lgkmcnt(0)
	v_pk_fma_f32 v[60:61], v[56:57], v[48:49], v[60:61] op_sel_hi:[1,0,1] neg_lo:[0,1,0] neg_hi:[0,1,0]
	v_pk_fma_f32 v[52:53], v[58:59], v[48:49], v[52:53] op_sel_hi:[1,0,1] neg_lo:[0,1,0] neg_hi:[0,1,0]
	v_pk_mul_f32 v[122:123], v[60:61], v[64:65]
	v_pk_fma_f32 v[122:123], v[52:53], v[66:67], v[122:123]
	v_add_f32_e32 v107, v122, v123
	v_add_f32_dpp v90, v90, v90 row_ror:8 row_mask:0xf bank_mask:0x3
	v_add_f32_dpp v91, v91, v91 row_ror:8 row_mask:0xf bank_mask:0x3
	v_add_f32_dpp v92, v92, v92 row_ror:8 row_mask:0xf bank_mask:0x3
	v_add_f32_dpp v93, v93, v93 row_ror:8 row_mask:0xf bank_mask:0x3
	v_add_f32_dpp v45, v45, v45 row_ror:8 row_mask:0xf bank_mask:0x3
	v_add_f32_dpp v46, v46, v46 row_ror:8 row_mask:0xf bank_mask:0x3
	v_add_f32_dpp v47, v47, v47 row_ror:8 row_mask:0xf bank_mask:0x3
	v_add_f32_dpp v50, v50, v50 row_ror:8 row_mask:0xf bank_mask:0x3
	v_add_f32_dpp v90, v51, v51 row_ror:8 row_mask:0xf bank_mask:0xc
	v_add_f32_dpp v91, v54, v54 row_ror:8 row_mask:0xf bank_mask:0xc
	v_add_f32_dpp v92, v55, v55 row_ror:8 row_mask:0xf bank_mask:0xc
	v_add_f32_dpp v93, v62, v62 row_ror:8 row_mask:0xf bank_mask:0xc
	v_add_f32_dpp v45, v63, v63 row_ror:8 row_mask:0xf bank_mask:0xc
	v_add_f32_dpp v46, v68, v68 row_ror:8 row_mask:0xf bank_mask:0xc
	v_add_f32_dpp v47, v88, v88 row_ror:8 row_mask:0xf bank_mask:0xc
	v_add_f32_dpp v50, v107, v107 row_ror:8 row_mask:0xf bank_mask:0xc
	v_add_f32_dpp v90, v90, v90 row_ror:12 row_mask:0xf bank_mask:0x5
	v_add_f32_dpp v91, v91, v91 row_ror:12 row_mask:0xf bank_mask:0x5
	v_add_f32_dpp v92, v92, v92 row_ror:12 row_mask:0xf bank_mask:0x5
	v_add_f32_dpp v93, v93, v93 row_ror:12 row_mask:0xf bank_mask:0x5
	v_add_f32_dpp v90, v45, v45 row_ror:4 row_mask:0xf bank_mask:0xa
	v_add_f32_dpp v91, v46, v46 row_ror:4 row_mask:0xf bank_mask:0xa
	v_add_f32_dpp v92, v47, v47 row_ror:4 row_mask:0xf bank_mask:0xa
	v_add_f32_dpp v93, v50, v50 row_ror:4 row_mask:0xf bank_mask:0xa
	s_mov_b32 vcc_lo, 0xcccccccc
	s_mov_b32 vcc_hi, 0xcccccccc
	v_cndmask_b32_e32 v51, v92, v90, vcc
	v_cndmask_b32_e32 v54, v93, v91, vcc
	v_cndmask_b32_e32 v55, v90, v92, vcc
	v_cndmask_b32_e32 v62, v91, v93, vcc
	v_add_f32_dpp v90, v51, v55 quad_perm:[2,3,0,1] row_mask:0xf bank_mask:0xf
	v_add_f32_dpp v91, v54, v62 quad_perm:[2,3,0,1] row_mask:0xf bank_mask:0xf
	s_mov_b32 vcc_lo, 0xaaaaaaaa
	s_mov_b32 vcc_hi, 0xaaaaaaaa
	v_cndmask_b32_e32 v51, v91, v90, vcc
	v_cndmask_b32_e32 v55, v90, v91, vcc
	s_nop 1
	v_add_f32_dpp v109, v51, v55 quad_perm:[1,0,3,2] row_mask:0xf bank_mask:0xf
.LBB0_1205:
	s_andn2_b64 vcc, exec, s[14:15]
	ds_write_b32 v98, v109 offset:44032
	s_cbranch_vccnz .LBB0_1186
	s_cmp_lg_u64 s[4:5], 0
	s_cbranch_scc1 .Lscan_wsa_w0
	s_waitcnt vmcnt(4)
	s_branch .Lscan_wsa_done
.Lscan_wsa_w0:
	s_waitcnt vmcnt(5)
.Lscan_wsa_done:
	v_lshlrev_b32_e32 v32, 16, v0
	v_and_b32_e32 v33, 0xffff0000, v0
	v_lshlrev_b32_e32 v34, 16, v1
	v_and_b32_e32 v35, 0xffff0000, v1
	v_lshlrev_b32_e32 v36, 16, v2
	v_and_b32_e32 v37, 0xffff0000, v2
	v_lshlrev_b32_e32 v38, 16, v3
	v_and_b32_e32 v39, 0xffff0000, v3
	ds_write_b128 v94, v[32:35]
	ds_write_b128 v94, v[36:39] offset:16
	v_lshlrev_b32_e32 v32, 16, v4
	v_and_b32_e32 v33, 0xffff0000, v4
	v_lshlrev_b32_e32 v34, 16, v5
	v_and_b32_e32 v35, 0xffff0000, v5
	v_lshlrev_b32_e32 v36, 16, v6
	v_and_b32_e32 v37, 0xffff0000, v6
	v_lshlrev_b32_e32 v38, 16, v7
	v_and_b32_e32 v39, 0xffff0000, v7
	ds_write_b128 v95, v[32:35]
	ds_write_b128 v95, v[36:39] offset:16
	ds_write_b128 v96, v[8:11]
	s_and_saveexec_b64 s[14:15], s[4:5]
	s_cbranch_execz .LBB0_1185
	v_lshlrev_b32_e32 v32, 16, v12
	v_and_b32_e32 v33, 0xffff0000, v12
	v_lshlrev_b32_e32 v34, 16, v13
	v_and_b32_e32 v35, 0xffff0000, v13
	v_lshlrev_b32_e32 v36, 16, v14
	v_and_b32_e32 v37, 0xffff0000, v14
	v_lshlrev_b32_e32 v38, 16, v15
	v_and_b32_e32 v39, 0xffff0000, v15
	ds_write_b128 v100, v[32:35] offset:1280
	ds_write_b128 v100, v[36:39] offset:1296
	s_branch .LBB0_1185
